# LRU GEMM epilogue: 16 x_conv row loads issued together; first down-GEMM epilogue (f32 residual source): loads hoisted and kept 7 steps ahead with counted waits
# baseline (speedup 1.0000x reference)
.LBB0_400:
	s_add_u32 s16, s14, 0x100
	s_addc_u32 s17, s15, 0
	s_add_i32 s49, 0, 0x10000
	v_add_u32_e32 v154, s49, v164
	ds_read_b128 v[142:145], v154
	ds_read_b128 v[146:149], v154 offset:1024
	ds_read_b128 v[150:153], v154 offset:2048
	ds_read_b128 v[154:157], v154 offset:3072
	s_cmp_eq_u32 s48, 40
	s_cselect_b32 s21, s7, s17
	s_cselect_b32 s20, s6, s16
	s_cselect_b32 s19, s9, s47
	s_cselect_b32 s18, s8, s46
	v_lshl_add_u64 v[162:163], s[14:15], 0, v[138:139]
	s_add_i32 m0, s34, 0xc000
	ds_read_b128 v[158:161], v166
	ds_read_b128 v[168:171], v166 offset:1024
	ds_read_b128 v[172:175], v166 offset:2048
	ds_read_b128 v[190:193], v166 offset:3072
	ds_read_b128 v[194:197], v166 offset:4096
	ds_read_b128 v[198:201], v166 offset:5120
	ds_read_b128 v[202:205], v166 offset:6144
	ds_read_b128 v[206:209], v166 offset:7168
	global_load_lds_dwordx4 v[162:163], off
	v_lshl_add_u64 v[162:163], s[14:15], 0, v[140:141]
	s_add_i32 m0, s34, 0xe000
	s_nop 0
	global_load_lds_dwordx4 v[162:163], off
	s_waitcnt lgkmcnt(8)
	s_barrier
	s_waitcnt lgkmcnt(0)
	s_waitcnt lgkmcnt(0)
	v_mfma_f32_16x16x32_bf16 v[126:129], v[142:145], v[158:161], v[126:129]
	v_mfma_f32_16x16x32_bf16 v[122:125], v[150:153], v[158:161], v[122:125]
	v_mfma_f32_16x16x32_bf16 v[110:113], v[142:145], v[172:175], v[110:113]
	v_mfma_f32_16x16x32_bf16 v[106:109], v[150:153], v[172:175], v[106:109]
	v_mfma_f32_16x16x32_bf16 v[94:97], v[142:145], v[194:197], v[94:97]
	v_mfma_f32_16x16x32_bf16 v[90:93], v[150:153], v[194:197], v[90:93]
	v_mfma_f32_16x16x32_bf16 v[78:81], v[142:145], v[202:205], v[78:81]
	v_mfma_f32_16x16x32_bf16 v[74:77], v[150:153], v[202:205], v[74:77]
	v_mfma_f32_16x16x32_bf16 v[126:129], v[146:149], v[168:171], v[126:129]
	v_mfma_f32_16x16x32_bf16 v[122:125], v[154:157], v[168:171], v[122:125]
	v_mfma_f32_16x16x32_bf16 v[110:113], v[146:149], v[190:193], v[110:113]
	v_mfma_f32_16x16x32_bf16 v[106:109], v[154:157], v[190:193], v[106:109]
	v_mfma_f32_16x16x32_bf16 v[94:97], v[146:149], v[198:201], v[94:97]
	v_mfma_f32_16x16x32_bf16 v[90:93], v[154:157], v[198:201], v[90:93]
	v_mfma_f32_16x16x32_bf16 v[78:81], v[146:149], v[206:209], v[78:81]
	v_mfma_f32_16x16x32_bf16 v[74:77], v[154:157], v[206:209], v[74:77]
	s_barrier
	s_add_i32 s50, 0, 0x14000
	v_add_u32_e32 v162, s50, v164
	s_add_i32 s14, s49, s33
	ds_read_b128 v[210:213], v162
	ds_read_b128 v[214:217], v162 offset:1024
	ds_read_b128 v[218:221], v162 offset:2048
	ds_read_b128 v[222:225], v162 offset:3072
	s_add_u32 s64, s18, 0x80
	s_addc_u32 s65, s19, 0
	s_mov_b32 m0, s14
	s_nop 0
	global_load_lds_dwordx4 v132, s[18:19]
	s_add_i32 m0, s14, 0x2000
	s_nop 0
	global_load_lds_dwordx4 v136, s[18:19]
	s_barrier
	s_waitcnt lgkmcnt(0)
	s_waitcnt lgkmcnt(0)
	v_mfma_f32_16x16x32_bf16 v[118:121], v[210:213], v[158:161], v[118:121]
	v_mfma_f32_16x16x32_bf16 v[114:117], v[218:221], v[158:161], v[114:117]
	v_mfma_f32_16x16x32_bf16 v[102:105], v[210:213], v[172:175], v[102:105]
	v_mfma_f32_16x16x32_bf16 v[98:101], v[218:221], v[172:175], v[98:101]
	v_mfma_f32_16x16x32_bf16 v[86:89], v[210:213], v[194:197], v[86:89]
	v_mfma_f32_16x16x32_bf16 v[82:85], v[218:221], v[194:197], v[82:85]
	v_mfma_f32_16x16x32_bf16 v[70:73], v[210:213], v[202:205], v[70:73]
	v_mfma_f32_16x16x32_bf16 v[66:69], v[218:221], v[202:205], v[66:69]
	v_mfma_f32_16x16x32_bf16 v[118:121], v[214:217], v[168:171], v[118:121]
	v_mfma_f32_16x16x32_bf16 v[114:117], v[222:225], v[168:171], v[114:117]
	v_mfma_f32_16x16x32_bf16 v[102:105], v[214:217], v[190:193], v[102:105]
	v_mfma_f32_16x16x32_bf16 v[98:101], v[222:225], v[190:193], v[98:101]
	v_mfma_f32_16x16x32_bf16 v[86:89], v[214:217], v[198:201], v[86:89]
	v_mfma_f32_16x16x32_bf16 v[82:85], v[222:225], v[198:201], v[82:85]
	v_mfma_f32_16x16x32_bf16 v[70:73], v[214:217], v[206:209], v[70:73]
	v_mfma_f32_16x16x32_bf16 v[66:69], v[222:225], v[206:209], v[66:69]
	s_barrier
	s_mov_b32 m0, s34
	s_add_u32 s62, s20, 0x80
	s_addc_u32 s63, s21, 0
	ds_read_b128 v[158:161], v166 offset:16384
	ds_read_b128 v[168:171], v166 offset:17408
	ds_read_b128 v[172:175], v166 offset:18432
	ds_read_b128 v[190:193], v166 offset:19456
	ds_read_b128 v[194:197], v166 offset:20480
	ds_read_b128 v[198:201], v166 offset:21504
	ds_read_b128 v[202:205], v166 offset:22528
	ds_read_b128 v[206:209], v166 offset:23552
	global_load_lds_dwordx4 v130, s[20:21]
	s_mov_b32 m0, s35
	s_nop 0
	global_load_lds_dwordx4 v134, s[20:21]
	s_barrier
	s_waitcnt lgkmcnt(0)
	s_waitcnt lgkmcnt(0)
	v_mfma_f32_16x16x32_bf16 v[62:65], v[142:145], v[158:161], v[62:65]
	v_mfma_f32_16x16x32_bf16 v[58:61], v[150:153], v[158:161], v[58:61]
	v_mfma_f32_16x16x32_bf16 v[46:49], v[142:145], v[172:175], v[46:49]
	v_mfma_f32_16x16x32_bf16 v[42:45], v[150:153], v[172:175], v[42:45]
	v_mfma_f32_16x16x32_bf16 v[30:33], v[142:145], v[194:197], v[30:33]
	v_mfma_f32_16x16x32_bf16 v[26:29], v[150:153], v[194:197], v[26:29]
	v_mfma_f32_16x16x32_bf16 v[14:17], v[142:145], v[202:205], v[14:17]
	v_mfma_f32_16x16x32_bf16 v[10:13], v[150:153], v[202:205], v[10:13]
	v_mfma_f32_16x16x32_bf16 v[62:65], v[146:149], v[168:171], v[62:65]
	v_mfma_f32_16x16x32_bf16 v[58:61], v[154:157], v[168:171], v[58:61]
	v_mfma_f32_16x16x32_bf16 v[46:49], v[146:149], v[190:193], v[46:49]
	v_mfma_f32_16x16x32_bf16 v[42:45], v[154:157], v[190:193], v[42:45]
	v_mfma_f32_16x16x32_bf16 v[30:33], v[146:149], v[198:201], v[30:33]
	v_mfma_f32_16x16x32_bf16 v[26:29], v[154:157], v[198:201], v[26:29]
	v_mfma_f32_16x16x32_bf16 v[14:17], v[146:149], v[206:209], v[14:17]
	v_mfma_f32_16x16x32_bf16 v[10:13], v[154:157], v[206:209], v[10:13]
	s_barrier
	s_add_u32 s14, s18, 0xb0000
	s_addc_u32 s15, s19, 0
	s_add_i32 s49, s50, s33
	s_mov_b32 m0, s49
	s_nop 0
	global_load_lds_dwordx4 v132, s[14:15]
	s_add_i32 m0, s49, 0x2000
	s_nop 0
	global_load_lds_dwordx4 v136, s[14:15]
	s_waitcnt vmcnt(6)
	s_barrier
	v_mfma_f32_16x16x32_bf16 v[54:57], v[210:213], v[158:161], v[54:57]
	v_mfma_f32_16x16x32_bf16 v[50:53], v[218:221], v[158:161], v[50:53]
	v_mfma_f32_16x16x32_bf16 v[38:41], v[210:213], v[172:175], v[38:41]
	v_mfma_f32_16x16x32_bf16 v[34:37], v[218:221], v[172:175], v[34:37]
	v_mfma_f32_16x16x32_bf16 v[22:25], v[210:213], v[194:197], v[22:25]
	v_mfma_f32_16x16x32_bf16 v[18:21], v[218:221], v[194:197], v[18:21]
	v_mfma_f32_16x16x32_bf16 v[6:9], v[210:213], v[202:205], v[6:9]
	v_mfma_f32_16x16x32_bf16 v[2:5], v[218:221], v[202:205], v[2:5]
	v_mfma_f32_16x16x32_bf16 v[54:57], v[214:217], v[168:171], v[54:57]
	v_mfma_f32_16x16x32_bf16 v[50:53], v[222:225], v[168:171], v[50:53]
	v_mfma_f32_16x16x32_bf16 v[38:41], v[214:217], v[190:193], v[38:41]
	v_mfma_f32_16x16x32_bf16 v[34:37], v[222:225], v[190:193], v[34:37]
	v_mfma_f32_16x16x32_bf16 v[22:25], v[214:217], v[198:201], v[22:25]
	v_mfma_f32_16x16x32_bf16 v[18:21], v[222:225], v[198:201], v[18:21]
	v_mfma_f32_16x16x32_bf16 v[6:9], v[214:217], v[206:209], v[6:9]
	v_mfma_f32_16x16x32_bf16 v[2:5], v[222:225], v[206:209], v[2:5]
	s_barrier
	s_add_i32 s49, 0, 0x18000
	v_add_u32_e32 v154, s49, v164
	ds_read_b128 v[142:145], v154
	ds_read_b128 v[146:149], v154 offset:1024
	ds_read_b128 v[150:153], v154 offset:2048
	ds_read_b128 v[154:157], v154 offset:3072
	s_add_u32 s14, s20, 0xb8000
	s_addc_u32 s15, s21, 0
	s_mov_b32 m0, s36
	ds_read_b128 v[158:161], v166 offset:32768
	ds_read_b128 v[168:171], v166 offset:33792
	ds_read_b128 v[172:175], v166 offset:34816
	ds_read_b128 v[190:193], v166 offset:35840
	ds_read_b128 v[194:197], v166 offset:36864
	ds_read_b128 v[198:201], v166 offset:37888
	ds_read_b128 v[202:205], v166 offset:38912
	ds_read_b128 v[206:209], v166 offset:39936
	global_load_lds_dwordx4 v130, s[14:15]
	s_mov_b32 m0, s37
	s_nop 0
	global_load_lds_dwordx4 v134, s[14:15]
	s_waitcnt lgkmcnt(8)
	s_barrier
	s_waitcnt lgkmcnt(0)
	s_waitcnt lgkmcnt(0)
	v_mfma_f32_16x16x32_bf16 v[126:129], v[142:145], v[158:161], v[126:129]
	v_mfma_f32_16x16x32_bf16 v[122:125], v[150:153], v[158:161], v[122:125]
	v_mfma_f32_16x16x32_bf16 v[110:113], v[142:145], v[172:175], v[110:113]
	v_mfma_f32_16x16x32_bf16 v[106:109], v[150:153], v[172:175], v[106:109]
	v_mfma_f32_16x16x32_bf16 v[94:97], v[142:145], v[194:197], v[94:97]
	v_mfma_f32_16x16x32_bf16 v[90:93], v[150:153], v[194:197], v[90:93]
	v_mfma_f32_16x16x32_bf16 v[78:81], v[142:145], v[202:205], v[78:81]
	v_mfma_f32_16x16x32_bf16 v[74:77], v[150:153], v[202:205], v[74:77]
	v_mfma_f32_16x16x32_bf16 v[126:129], v[146:149], v[168:171], v[126:129]
	v_mfma_f32_16x16x32_bf16 v[122:125], v[154:157], v[168:171], v[122:125]
	v_mfma_f32_16x16x32_bf16 v[110:113], v[146:149], v[190:193], v[110:113]
	v_mfma_f32_16x16x32_bf16 v[106:109], v[154:157], v[190:193], v[106:109]
	v_mfma_f32_16x16x32_bf16 v[94:97], v[146:149], v[198:201], v[94:97]
	v_mfma_f32_16x16x32_bf16 v[90:93], v[154:157], v[198:201], v[90:93]
	v_mfma_f32_16x16x32_bf16 v[78:81], v[146:149], v[206:209], v[78:81]
	v_mfma_f32_16x16x32_bf16 v[74:77], v[154:157], v[206:209], v[74:77]
	s_barrier
	s_add_i32 s20, 0, 0x1c000
	s_add_i32 s14, s49, s33
	v_add_u32_e32 v167, s20, v164
	s_mov_b32 m0, s14
	ds_read_b128 v[210:213], v167
	ds_read_b128 v[214:217], v167 offset:1024
	ds_read_b128 v[218:221], v167 offset:2048
	ds_read_b128 v[222:225], v167 offset:3072
	global_load_lds_dwordx4 v132, s[64:65]
	s_add_i32 m0, s14, 0x2000
	s_nop 0
	global_load_lds_dwordx4 v136, s[64:65]
	s_barrier
	s_waitcnt lgkmcnt(0)
	s_waitcnt lgkmcnt(0)
	v_mfma_f32_16x16x32_bf16 v[118:121], v[210:213], v[158:161], v[118:121]
	v_mfma_f32_16x16x32_bf16 v[114:117], v[218:221], v[158:161], v[114:117]
	v_mfma_f32_16x16x32_bf16 v[102:105], v[210:213], v[172:175], v[102:105]
	v_mfma_f32_16x16x32_bf16 v[98:101], v[218:221], v[172:175], v[98:101]
	v_mfma_f32_16x16x32_bf16 v[86:89], v[210:213], v[194:197], v[86:89]
	v_mfma_f32_16x16x32_bf16 v[82:85], v[218:221], v[194:197], v[82:85]
	v_mfma_f32_16x16x32_bf16 v[70:73], v[210:213], v[202:205], v[70:73]
	v_mfma_f32_16x16x32_bf16 v[66:69], v[218:221], v[202:205], v[66:69]
	v_mfma_f32_16x16x32_bf16 v[118:121], v[214:217], v[168:171], v[118:121]
	v_mfma_f32_16x16x32_bf16 v[114:117], v[222:225], v[168:171], v[114:117]
	v_mfma_f32_16x16x32_bf16 v[102:105], v[214:217], v[190:193], v[102:105]
	v_mfma_f32_16x16x32_bf16 v[98:101], v[222:225], v[190:193], v[98:101]
	v_mfma_f32_16x16x32_bf16 v[86:89], v[214:217], v[198:201], v[86:89]
	v_mfma_f32_16x16x32_bf16 v[82:85], v[222:225], v[198:201], v[82:85]
	v_mfma_f32_16x16x32_bf16 v[70:73], v[214:217], v[206:209], v[70:73]
	v_mfma_f32_16x16x32_bf16 v[66:69], v[222:225], v[206:209], v[66:69]
	s_barrier
	s_mov_b32 m0, s38
	ds_read_b128 v[158:161], v166 offset:49152
	ds_read_b128 v[168:171], v166 offset:50176
	ds_read_b128 v[172:175], v166 offset:51200
	ds_read_b128 v[190:193], v166 offset:52224
	ds_read_b128 v[194:197], v166 offset:53248
	ds_read_b128 v[198:201], v166 offset:54272
	ds_read_b128 v[202:205], v166 offset:55296
	ds_read_b128 v[206:209], v166 offset:56320
	global_load_lds_dwordx4 v130, s[62:63]
	s_mov_b32 m0, s39
	s_nop 0
	global_load_lds_dwordx4 v134, s[62:63]
	s_barrier
	s_waitcnt lgkmcnt(0)
	s_waitcnt lgkmcnt(0)
	v_mfma_f32_16x16x32_bf16 v[62:65], v[142:145], v[158:161], v[62:65]
	v_mfma_f32_16x16x32_bf16 v[58:61], v[150:153], v[158:161], v[58:61]
	v_mfma_f32_16x16x32_bf16 v[46:49], v[142:145], v[172:175], v[46:49]
	v_mfma_f32_16x16x32_bf16 v[42:45], v[150:153], v[172:175], v[42:45]
	v_mfma_f32_16x16x32_bf16 v[30:33], v[142:145], v[194:197], v[30:33]
	v_mfma_f32_16x16x32_bf16 v[26:29], v[150:153], v[194:197], v[26:29]
	v_mfma_f32_16x16x32_bf16 v[14:17], v[142:145], v[202:205], v[14:17]
	v_mfma_f32_16x16x32_bf16 v[10:13], v[150:153], v[202:205], v[10:13]
	v_mfma_f32_16x16x32_bf16 v[62:65], v[146:149], v[168:171], v[62:65]
	v_mfma_f32_16x16x32_bf16 v[58:61], v[154:157], v[168:171], v[58:61]
	v_mfma_f32_16x16x32_bf16 v[46:49], v[146:149], v[190:193], v[46:49]
	v_mfma_f32_16x16x32_bf16 v[42:45], v[154:157], v[190:193], v[42:45]
	v_mfma_f32_16x16x32_bf16 v[30:33], v[146:149], v[198:201], v[30:33]
	v_mfma_f32_16x16x32_bf16 v[26:29], v[154:157], v[198:201], v[26:29]
	v_mfma_f32_16x16x32_bf16 v[14:17], v[146:149], v[206:209], v[14:17]
	v_mfma_f32_16x16x32_bf16 v[10:13], v[154:157], v[206:209], v[10:13]
	s_barrier
	s_add_u32 s14, s18, 0xb0080
	s_addc_u32 s15, s19, 0
	s_add_i32 s18, s20, s33
	s_mov_b32 m0, s18
	s_nop 0
	global_load_lds_dwordx4 v132, s[14:15]
	s_add_i32 m0, s18, 0x2000
	s_nop 0
	global_load_lds_dwordx4 v136, s[14:15]
	s_waitcnt vmcnt(6)
	s_barrier
	v_mfma_f32_16x16x32_bf16 v[54:57], v[210:213], v[158:161], v[54:57]
	v_mfma_f32_16x16x32_bf16 v[50:53], v[218:221], v[158:161], v[50:53]
	v_mfma_f32_16x16x32_bf16 v[38:41], v[210:213], v[172:175], v[38:41]
	v_mfma_f32_16x16x32_bf16 v[34:37], v[218:221], v[172:175], v[34:37]
	v_mfma_f32_16x16x32_bf16 v[22:25], v[210:213], v[194:197], v[22:25]
	v_mfma_f32_16x16x32_bf16 v[18:21], v[218:221], v[194:197], v[18:21]
	v_mfma_f32_16x16x32_bf16 v[6:9], v[210:213], v[202:205], v[6:9]
	v_mfma_f32_16x16x32_bf16 v[2:5], v[218:221], v[202:205], v[2:5]
	v_mfma_f32_16x16x32_bf16 v[54:57], v[214:217], v[168:171], v[54:57]
	v_mfma_f32_16x16x32_bf16 v[50:53], v[222:225], v[168:171], v[50:53]
	v_mfma_f32_16x16x32_bf16 v[38:41], v[214:217], v[190:193], v[38:41]
	v_mfma_f32_16x16x32_bf16 v[34:37], v[222:225], v[190:193], v[34:37]
	v_mfma_f32_16x16x32_bf16 v[22:25], v[214:217], v[198:201], v[22:25]
	v_mfma_f32_16x16x32_bf16 v[18:21], v[222:225], v[198:201], v[18:21]
	v_mfma_f32_16x16x32_bf16 v[6:9], v[214:217], v[206:209], v[6:9]
	v_mfma_f32_16x16x32_bf16 v[2:5], v[222:225], v[206:209], v[2:5]
	s_barrier
	s_add_i32 s48, s48, 2
	s_add_u32 s46, s46, 0x100
	s_addc_u32 s47, s47, 0
	s_cmp_gt_u32 s48, 41
	s_mov_b64 s[14:15], s[16:17]
	s_cbranch_scc0 .LBB0_400
	s_ashr_i32 s14, s44, 5
	v_lshl_or_b32 v176, s45, 8, v165
	s_mul_hi_i32 s15, s14, 0x9000
	s_mul_i32 s14, s14, 0x9000
	s_add_u32 s14, s26, s14
	v_ashrrev_i32_e32 v177, 31, v176
	s_addc_u32 s15, s27, s15
	v_lshlrev_b64 v[158:159], 2, v[176:177]
	v_lshl_add_u64 v[160:161], s[14:15], 0, v[158:159]
	global_load_dwordx4 v[142:145], v[160:161], off offset:16
	global_load_dwordx4 v[146:149], v[160:161], off
	v_lshl_add_u32 v162, s44, 8, v1
	v_ashrrev_i32_e32 v163, 31, v162
	v_lshl_add_u32 v131, v162, 12, v158
	global_load_dwordx4 v[188:191], v131, s[2:3] offset:16
	global_load_dwordx4 v[192:195], v131, s[2:3]
	global_load_dwordx4 v[196:199], v131, s[2:3] offset:528
	global_load_dwordx4 v[200:203], v131, s[2:3] offset:512
	v_add_u32_e32 v131, 0x10000, v131
	global_load_dwordx4 v[204:207], v131, s[2:3] offset:16
	global_load_dwordx4 v[208:211], v131, s[2:3]
	global_load_dwordx4 v[212:215], v131, s[2:3] offset:528
	global_load_dwordx4 v[216:219], v131, s[2:3] offset:512
	v_add_u32_e32 v131, 0x10000, v131
	global_load_dwordx4 v[220:223], v131, s[2:3] offset:16
	global_load_dwordx4 v[224:227], v131, s[2:3]
	global_load_dwordx4 v[228:231], v131, s[2:3] offset:528
	global_load_dwordx4 v[236:239], v131, s[2:3] offset:512
	v_add_u32_e32 v131, 0x10000, v131
	global_load_dwordx4 v[246:249], v131, s[2:3] offset:16
	global_load_dwordx4 v[250:253], v131, s[2:3]
	v_mov_b32_e32 v133, v131
	s_mov_b64 s[14:15], 0x80000
	s_and_b64 vcc, exec, s[4:5]
	s_mov_b32 s45, s42
	s_mov_b32 s44, s43
	s_mov_b64 s[16:17], s[8:9]
	s_waitcnt vmcnt(0)
	v_pk_add_f32 v[144:145], v[144:145], 1.0 op_sel_hi:[1,0]
	v_pk_add_f32 v[148:149], v[148:149], 1.0 op_sel_hi:[1,0]
	v_pk_add_f32 v[146:147], v[146:147], 1.0 op_sel_hi:[1,0]
	v_pk_add_f32 v[142:143], v[142:143], 1.0 op_sel_hi:[1,0]
	v_pk_mul_f32 v[150:151], v[148:149], 0.5 op_sel_hi:[1,0]
	v_pk_mul_f32 v[152:153], v[146:147], 0.5 op_sel_hi:[1,0]
	v_pk_mul_f32 v[154:155], v[144:145], 0.5 op_sel_hi:[1,0]
	v_pk_mul_f32 v[156:157], v[142:143], 0.5 op_sel_hi:[1,0]
	global_load_dwordx4 v[146:149], v[160:161], off offset:528
	global_load_dwordx4 v[142:145], v[160:161], off offset:512
	s_waitcnt vmcnt(0)
	v_pk_add_f32 v[148:149], v[148:149], 1.0 op_sel_hi:[1,0]
	v_pk_add_f32 v[144:145], v[144:145], 1.0 op_sel_hi:[1,0]
	v_pk_add_f32 v[160:161], v[142:143], 1.0 op_sel_hi:[1,0]
	v_pk_mul_f32 v[142:143], v[144:145], 0.5 op_sel_hi:[1,0]
	v_pk_mul_f32 v[144:145], v[160:161], 0.5 op_sel_hi:[1,0]
	v_pk_add_f32 v[160:161], v[146:147], 1.0 op_sel_hi:[1,0]
	v_pk_mul_f32 v[146:147], v[148:149], 0.5 op_sel_hi:[1,0]
	v_pk_mul_f32 v[148:149], v[160:161], 0.5 op_sel_hi:[1,0]
	v_lshlrev_b64 v[160:161], 12, v[162:163]
	v_lshl_add_u64 v[168:169], s[2:3], 0, v[160:161]
	v_lshl_add_u64 v[186:187], v[168:169], 0, v[158:159]
	v_mov_b32_e32 v168, v188
	v_mov_b32_e32 v169, v189
	v_mov_b32_e32 v170, v190
	v_mov_b32_e32 v171, v191
	v_mov_b32_e32 v172, v192
	v_mov_b32_e32 v173, v193
	v_mov_b32_e32 v174, v194
	v_mov_b32_e32 v175, v195
	global_load_dwordx4 v[188:191], v133, s[2:3] offset:528
	global_load_dwordx4 v[192:195], v133, s[2:3] offset:512
	v_pk_fma_f32 v[122:123], v[122:123], v[156:157], v[168:169]
	v_pk_fma_f32 v[128:129], v[128:129], v[150:151], v[174:175]
	v_pk_fma_f32 v[126:127], v[126:127], v[152:153], v[172:173]
	v_pk_fma_f32 v[170:171], v[124:125], v[154:155], v[170:171]
	v_cvt_pk_bf16_f32 v124, v126, v127
	v_cvt_pk_bf16_f32 v125, v128, v129
	v_cvt_pk_bf16_f32 v126, v122, v123
	v_lshl_add_u64 v[128:129], s[12:13], 0, v[160:161]
	v_lshlrev_b64 v[122:123], 1, v[176:177]
	v_cvt_pk_bf16_f32 v127, v170, v171
	v_lshl_add_u64 v[128:129], v[128:129], 0, v[122:123]
	global_store_dwordx4 v[128:129], v[124:127], off offset:2048
	s_nop 1
	v_mov_b32_e32 v124, v196
	v_mov_b32_e32 v125, v197
	v_mov_b32_e32 v126, v198
	v_mov_b32_e32 v127, v199
	s_nop 0
	v_mov_b32_e32 v168, v200
	v_mov_b32_e32 v169, v201
	v_mov_b32_e32 v170, v202
	v_mov_b32_e32 v171, v203
	v_add_u32_e32 v133, 0x50000, v133
	global_load_dwordx4 v[196:199], v133, s[2:3] offset:16
	global_load_dwordx4 v[200:203], v133, s[2:3]
	v_pk_fma_f32 v[126:127], v[116:117], v[146:147], v[126:127]
	v_pk_fma_f32 v[120:121], v[120:121], v[142:143], v[170:171]
	v_pk_fma_f32 v[118:119], v[118:119], v[144:145], v[168:169]
	v_pk_fma_f32 v[116:117], v[114:115], v[148:149], v[124:125]
	v_cvt_pk_bf16_f32 v114, v118, v119
	v_cvt_pk_bf16_f32 v115, v120, v121
	v_cvt_pk_bf16_f32 v116, v116, v117
	v_cvt_pk_bf16_f32 v117, v126, v127
	global_store_dwordx4 v[128:129], v[114:117], off offset:2304
	s_nop 1
	v_or_b32_e32 v114, 16, v162
	v_ashrrev_i32_e32 v115, 31, v114
	v_lshlrev_b64 v[124:125], 12, v[114:115]
	v_lshl_add_u64 v[114:115], s[2:3], 0, v[124:125]
	v_lshl_add_u64 v[126:127], v[114:115], 0, v[158:159]
	v_mov_b32_e32 v114, v204
	v_mov_b32_e32 v115, v205
	v_mov_b32_e32 v116, v206
	v_mov_b32_e32 v117, v207
	v_mov_b32_e32 v118, v208
	v_mov_b32_e32 v119, v209
	v_mov_b32_e32 v120, v210
	v_mov_b32_e32 v121, v211
	global_load_dwordx4 v[204:207], v133, s[2:3] offset:528
	global_load_dwordx4 v[208:211], v133, s[2:3] offset:512
	v_pk_fma_f32 v[116:117], v[108:109], v[154:155], v[116:117]
	v_pk_fma_f32 v[110:111], v[110:111], v[152:153], v[118:119]
	v_pk_fma_f32 v[112:113], v[112:113], v[150:151], v[120:121]
	v_pk_fma_f32 v[108:109], v[106:107], v[156:157], v[114:115]
	v_cvt_pk_bf16_f32 v106, v110, v111
	v_lshl_add_u64 v[110:111], s[12:13], 0, v[124:125]
	v_cvt_pk_bf16_f32 v107, v112, v113
	v_cvt_pk_bf16_f32 v108, v108, v109
	v_cvt_pk_bf16_f32 v109, v116, v117
	v_lshl_add_u64 v[114:115], v[110:111], 0, v[122:123]
	global_store_dwordx4 v[114:115], v[106:109], off offset:2048
	s_nop 1
	v_mov_b32_e32 v106, v212
	v_mov_b32_e32 v107, v213
	v_mov_b32_e32 v108, v214
	v_mov_b32_e32 v109, v215
	s_nop 0
	v_mov_b32_e32 v110, v216
	v_mov_b32_e32 v111, v217
	v_mov_b32_e32 v112, v218
	v_mov_b32_e32 v113, v219
	v_add_u32_e32 v133, 0x10000, v133
	global_load_dwordx4 v[212:215], v133, s[2:3] offset:16
	global_load_dwordx4 v[216:219], v133, s[2:3]
	v_pk_fma_f32 v[108:109], v[100:101], v[146:147], v[108:109]
	v_pk_fma_f32 v[104:105], v[104:105], v[142:143], v[112:113]
	v_pk_fma_f32 v[102:103], v[102:103], v[144:145], v[110:111]
	v_pk_fma_f32 v[100:101], v[98:99], v[148:149], v[106:107]
	v_cvt_pk_bf16_f32 v98, v102, v103
	v_cvt_pk_bf16_f32 v99, v104, v105
	v_cvt_pk_bf16_f32 v100, v100, v101
	v_cvt_pk_bf16_f32 v101, v108, v109
	global_store_dwordx4 v[114:115], v[98:101], off offset:2304
	s_nop 1
	v_or_b32_e32 v98, 32, v162
	v_ashrrev_i32_e32 v99, 31, v98
	v_lshlrev_b64 v[106:107], 12, v[98:99]
	v_lshl_add_u64 v[98:99], s[2:3], 0, v[106:107]
	v_lshl_add_u64 v[108:109], v[98:99], 0, v[158:159]
	v_mov_b32_e32 v98, v220
	v_mov_b32_e32 v99, v221
	v_mov_b32_e32 v100, v222
	v_mov_b32_e32 v101, v223
	v_mov_b32_e32 v102, v224
	v_mov_b32_e32 v103, v225
	v_mov_b32_e32 v104, v226
	v_mov_b32_e32 v105, v227
	global_load_dwordx4 v[220:223], v133, s[2:3] offset:528
	global_load_dwordx4 v[224:227], v133, s[2:3] offset:512
	v_pk_fma_f32 v[100:101], v[92:93], v[154:155], v[100:101]
	v_pk_fma_f32 v[94:95], v[94:95], v[152:153], v[102:103]
	v_pk_fma_f32 v[96:97], v[96:97], v[150:151], v[104:105]
	v_pk_fma_f32 v[92:93], v[90:91], v[156:157], v[98:99]
	v_cvt_pk_bf16_f32 v90, v94, v95
	v_lshl_add_u64 v[94:95], s[12:13], 0, v[106:107]
	v_cvt_pk_bf16_f32 v91, v96, v97
	v_cvt_pk_bf16_f32 v92, v92, v93
	v_cvt_pk_bf16_f32 v93, v100, v101
	v_lshl_add_u64 v[98:99], v[94:95], 0, v[122:123]
	global_store_dwordx4 v[98:99], v[90:93], off offset:2048
	s_nop 1
	v_mov_b32_e32 v90, v228
	v_mov_b32_e32 v91, v229
	v_mov_b32_e32 v92, v230
	v_mov_b32_e32 v93, v231
	s_nop 0
	v_mov_b32_e32 v94, v236
	v_mov_b32_e32 v95, v237
	v_mov_b32_e32 v96, v238
	v_mov_b32_e32 v97, v239
	v_add_u32_e32 v133, 0x10000, v133
	global_load_dwordx4 v[228:231], v133, s[2:3] offset:16
	global_load_dwordx4 v[236:239], v133, s[2:3]
	v_pk_fma_f32 v[92:93], v[84:85], v[146:147], v[92:93]
	v_pk_fma_f32 v[88:89], v[88:89], v[142:143], v[96:97]
	v_pk_fma_f32 v[86:87], v[86:87], v[144:145], v[94:95]
	v_pk_fma_f32 v[84:85], v[82:83], v[148:149], v[90:91]
	v_cvt_pk_bf16_f32 v82, v86, v87
	v_cvt_pk_bf16_f32 v83, v88, v89
	v_cvt_pk_bf16_f32 v84, v84, v85
	v_cvt_pk_bf16_f32 v85, v92, v93
	global_store_dwordx4 v[98:99], v[82:85], off offset:2304
	s_nop 1
	v_or_b32_e32 v82, 48, v162
	v_ashrrev_i32_e32 v83, 31, v82
	v_lshlrev_b64 v[90:91], 12, v[82:83]
	v_lshl_add_u64 v[82:83], s[2:3], 0, v[90:91]
	v_lshl_add_u64 v[92:93], v[82:83], 0, v[158:159]
	v_mov_b32_e32 v82, v246
	v_mov_b32_e32 v83, v247
	v_mov_b32_e32 v84, v248
	v_mov_b32_e32 v85, v249
	v_mov_b32_e32 v86, v250
	v_mov_b32_e32 v87, v251
	v_mov_b32_e32 v88, v252
	v_mov_b32_e32 v89, v253
	global_load_dwordx4 v[246:249], v133, s[2:3] offset:528
	global_load_dwordx4 v[250:253], v133, s[2:3] offset:512
	v_pk_fma_f32 v[84:85], v[76:77], v[154:155], v[84:85]
	v_pk_fma_f32 v[78:79], v[78:79], v[152:153], v[86:87]
	v_pk_fma_f32 v[80:81], v[80:81], v[150:151], v[88:89]
	v_pk_fma_f32 v[76:77], v[74:75], v[156:157], v[82:83]
	v_cvt_pk_bf16_f32 v74, v78, v79
	v_lshl_add_u64 v[78:79], s[12:13], 0, v[90:91]
	v_cvt_pk_bf16_f32 v75, v80, v81
	v_cvt_pk_bf16_f32 v76, v76, v77
	v_cvt_pk_bf16_f32 v77, v84, v85
	v_lshl_add_u64 v[82:83], v[78:79], 0, v[122:123]
	global_store_dwordx4 v[82:83], v[74:77], off offset:2048
	s_nop 1
	s_waitcnt vmcnt(19)
	v_mov_b32_e32 v74, v188
	v_mov_b32_e32 v75, v189
	v_mov_b32_e32 v76, v190
	v_mov_b32_e32 v77, v191
	s_nop 0
	v_mov_b32_e32 v78, v192
	v_mov_b32_e32 v79, v193
	v_mov_b32_e32 v80, v194
	v_mov_b32_e32 v81, v195
	v_add_u32_e32 v133, 0x10000, v133
	global_load_dwordx4 v[188:191], v133, s[2:3] offset:16
	global_load_dwordx4 v[192:195], v133, s[2:3]
	v_pk_fma_f32 v[76:77], v[68:69], v[146:147], v[76:77]
	v_pk_fma_f32 v[72:73], v[72:73], v[142:143], v[80:81]
	v_pk_fma_f32 v[70:71], v[70:71], v[144:145], v[78:79]
	v_pk_fma_f32 v[68:69], v[66:67], v[148:149], v[74:75]
	v_cvt_pk_bf16_f32 v66, v70, v71
	v_cvt_pk_bf16_f32 v67, v72, v73
	v_cvt_pk_bf16_f32 v68, v68, v69
	v_cvt_pk_bf16_f32 v69, v76, v77
	v_lshl_add_u64 v[74:75], v[160:161], 0, s[14:15]
	global_store_dwordx4 v[82:83], v[66:69], off offset:2304
	s_mov_b64 s[14:15], 0x90000
	s_nop 0
	v_lshl_add_u64 v[66:67], s[2:3], 0, v[74:75]
	v_lshl_add_u64 v[76:77], v[66:67], 0, v[158:159]
	s_waitcnt vmcnt(19)
	v_mov_b32_e32 v66, v196
	v_mov_b32_e32 v67, v197
	v_mov_b32_e32 v68, v198
	v_mov_b32_e32 v69, v199
	v_mov_b32_e32 v70, v200
	v_mov_b32_e32 v71, v201
	v_mov_b32_e32 v72, v202
	v_mov_b32_e32 v73, v203
	global_load_dwordx4 v[196:199], v133, s[2:3] offset:528
	global_load_dwordx4 v[200:203], v133, s[2:3] offset:512
	v_pk_fma_f32 v[68:69], v[60:61], v[154:155], v[68:69]
	v_pk_fma_f32 v[62:63], v[62:63], v[152:153], v[70:71]
	v_pk_fma_f32 v[64:65], v[64:65], v[150:151], v[72:73]
	v_pk_fma_f32 v[60:61], v[58:59], v[156:157], v[66:67]
	v_cvt_pk_bf16_f32 v58, v62, v63
	v_lshl_add_u64 v[62:63], s[12:13], 0, v[74:75]
	v_cvt_pk_bf16_f32 v59, v64, v65
	v_cvt_pk_bf16_f32 v60, v60, v61
	v_cvt_pk_bf16_f32 v61, v68, v69
	v_lshl_add_u64 v[66:67], v[62:63], 0, v[122:123]
	global_store_dwordx4 v[66:67], v[58:61], off offset:2048
	s_nop 1
	s_waitcnt vmcnt(19)
	v_mov_b32_e32 v58, v204
	v_mov_b32_e32 v59, v205
	v_mov_b32_e32 v60, v206
	v_mov_b32_e32 v61, v207
	s_nop 0
	v_mov_b32_e32 v62, v208
	v_mov_b32_e32 v63, v209
	v_mov_b32_e32 v64, v210
	v_mov_b32_e32 v65, v211
	s_nop 0
	v_pk_fma_f32 v[60:61], v[52:53], v[146:147], v[60:61]
	v_pk_fma_f32 v[56:57], v[56:57], v[142:143], v[64:65]
	v_pk_fma_f32 v[54:55], v[54:55], v[144:145], v[62:63]
	v_pk_fma_f32 v[52:53], v[50:51], v[148:149], v[58:59]
	v_cvt_pk_bf16_f32 v50, v54, v55
	v_cvt_pk_bf16_f32 v51, v56, v57
	v_cvt_pk_bf16_f32 v52, v52, v53
	v_cvt_pk_bf16_f32 v53, v60, v61
	v_lshl_add_u64 v[58:59], v[160:161], 0, s[14:15]
	global_store_dwordx4 v[66:67], v[50:53], off offset:2304
	s_mov_b64 s[14:15], 0xa0000
	s_nop 0
	v_lshl_add_u64 v[50:51], s[2:3], 0, v[58:59]
	v_lshl_add_u64 v[60:61], v[50:51], 0, v[158:159]
	s_waitcnt vmcnt(17)
	v_mov_b32_e32 v50, v212
	v_mov_b32_e32 v51, v213
	v_mov_b32_e32 v52, v214
	v_mov_b32_e32 v53, v215
	v_mov_b32_e32 v54, v216
	v_mov_b32_e32 v55, v217
	v_mov_b32_e32 v56, v218
	v_mov_b32_e32 v57, v219
	s_nop 0
	v_pk_fma_f32 v[52:53], v[44:45], v[154:155], v[52:53]
	v_pk_fma_f32 v[46:47], v[46:47], v[152:153], v[54:55]
	v_pk_fma_f32 v[48:49], v[48:49], v[150:151], v[56:57]
	v_pk_fma_f32 v[44:45], v[42:43], v[156:157], v[50:51]
	v_cvt_pk_bf16_f32 v42, v46, v47
	v_lshl_add_u64 v[46:47], s[12:13], 0, v[58:59]
	v_cvt_pk_bf16_f32 v43, v48, v49
	v_cvt_pk_bf16_f32 v44, v44, v45
	v_cvt_pk_bf16_f32 v45, v52, v53
	v_lshl_add_u64 v[50:51], v[46:47], 0, v[122:123]
	global_store_dwordx4 v[50:51], v[42:45], off offset:2048
	s_nop 1
	s_waitcnt vmcnt(15)
	v_mov_b32_e32 v42, v220
	v_mov_b32_e32 v43, v221
	v_mov_b32_e32 v44, v222
	v_mov_b32_e32 v45, v223
	s_nop 0
	v_mov_b32_e32 v46, v224
	v_mov_b32_e32 v47, v225
	v_mov_b32_e32 v48, v226
	v_mov_b32_e32 v49, v227
	s_nop 0
	v_pk_fma_f32 v[44:45], v[36:37], v[146:147], v[44:45]
	v_pk_fma_f32 v[40:41], v[40:41], v[142:143], v[48:49]
	v_pk_fma_f32 v[38:39], v[38:39], v[144:145], v[46:47]
	v_pk_fma_f32 v[36:37], v[34:35], v[148:149], v[42:43]
	v_cvt_pk_bf16_f32 v34, v38, v39
	v_cvt_pk_bf16_f32 v35, v40, v41
	v_cvt_pk_bf16_f32 v36, v36, v37
	v_cvt_pk_bf16_f32 v37, v44, v45
	v_lshl_add_u64 v[42:43], v[160:161], 0, s[14:15]
	global_store_dwordx4 v[50:51], v[34:37], off offset:2304
	s_mov_b64 s[14:15], 0xb0000
	s_nop 0
	v_lshl_add_u64 v[34:35], s[2:3], 0, v[42:43]
	v_lshl_add_u64 v[44:45], v[34:35], 0, v[158:159]
	s_waitcnt vmcnt(13)
	v_mov_b32_e32 v34, v228
	v_mov_b32_e32 v35, v229
	v_mov_b32_e32 v36, v230
	v_mov_b32_e32 v37, v231
	v_mov_b32_e32 v38, v236
	v_mov_b32_e32 v39, v237
	v_mov_b32_e32 v40, v238
	v_mov_b32_e32 v41, v239
	s_nop 0
	v_pk_fma_f32 v[36:37], v[28:29], v[154:155], v[36:37]
	v_pk_fma_f32 v[30:31], v[30:31], v[152:153], v[38:39]
	v_pk_fma_f32 v[32:33], v[32:33], v[150:151], v[40:41]
	v_pk_fma_f32 v[28:29], v[26:27], v[156:157], v[34:35]
	v_cvt_pk_bf16_f32 v26, v30, v31
	v_lshl_add_u64 v[30:31], s[12:13], 0, v[42:43]
	v_cvt_pk_bf16_f32 v27, v32, v33
	v_cvt_pk_bf16_f32 v28, v28, v29
	v_cvt_pk_bf16_f32 v29, v36, v37
	v_lshl_add_u64 v[34:35], v[30:31], 0, v[122:123]
	global_store_dwordx4 v[34:35], v[26:29], off offset:2048
	s_nop 1
	s_waitcnt vmcnt(11)
	v_mov_b32_e32 v26, v246
	v_mov_b32_e32 v27, v247
	v_mov_b32_e32 v28, v248
	v_mov_b32_e32 v29, v249
	s_nop 0
	v_mov_b32_e32 v30, v250
	v_mov_b32_e32 v31, v251
	v_mov_b32_e32 v32, v252
	v_mov_b32_e32 v33, v253
	s_nop 0
	v_pk_fma_f32 v[28:29], v[20:21], v[146:147], v[28:29]
	v_pk_fma_f32 v[24:25], v[24:25], v[142:143], v[32:33]
	v_pk_fma_f32 v[22:23], v[22:23], v[144:145], v[30:31]
	v_pk_fma_f32 v[20:21], v[18:19], v[148:149], v[26:27]
	v_cvt_pk_bf16_f32 v18, v22, v23
	v_cvt_pk_bf16_f32 v19, v24, v25
	v_cvt_pk_bf16_f32 v20, v20, v21
	v_cvt_pk_bf16_f32 v21, v28, v29
	v_lshl_add_u64 v[26:27], v[160:161], 0, s[14:15]
	global_store_dwordx4 v[34:35], v[18:21], off offset:2304
	s_mov_b64 s[14:15], s[6:7]
	s_nop 0
	v_lshl_add_u64 v[18:19], s[2:3], 0, v[26:27]
	v_lshl_add_u64 v[28:29], v[18:19], 0, v[158:159]
	s_waitcnt vmcnt(9)
	v_mov_b32_e32 v18, v188
	v_mov_b32_e32 v19, v189
	v_mov_b32_e32 v20, v190
	v_mov_b32_e32 v21, v191
	v_mov_b32_e32 v22, v192
	v_mov_b32_e32 v23, v193
	v_mov_b32_e32 v24, v194
	v_mov_b32_e32 v25, v195
	s_nop 0
	v_pk_fma_f32 v[20:21], v[12:13], v[154:155], v[20:21]
	v_pk_fma_f32 v[14:15], v[14:15], v[152:153], v[22:23]
	v_pk_fma_f32 v[16:17], v[16:17], v[150:151], v[24:25]
	v_pk_fma_f32 v[12:13], v[10:11], v[156:157], v[18:19]
	v_cvt_pk_bf16_f32 v10, v14, v15
	v_lshl_add_u64 v[14:15], s[12:13], 0, v[26:27]
	v_cvt_pk_bf16_f32 v11, v16, v17
	v_cvt_pk_bf16_f32 v12, v12, v13
	v_cvt_pk_bf16_f32 v13, v20, v21
	v_lshl_add_u64 v[18:19], v[14:15], 0, v[122:123]
	global_store_dwordx4 v[18:19], v[10:13], off offset:2048
	s_nop 1
	s_waitcnt vmcnt(7)
	v_mov_b32_e32 v10, v196
	v_mov_b32_e32 v11, v197
	v_mov_b32_e32 v12, v198
	v_mov_b32_e32 v13, v199
	s_nop 0
	v_mov_b32_e32 v14, v200
	v_mov_b32_e32 v15, v201
	v_mov_b32_e32 v16, v202
	v_mov_b32_e32 v17, v203
	s_nop 0
	v_pk_fma_f32 v[12:13], v[4:5], v[146:147], v[12:13]
	v_pk_fma_f32 v[8:9], v[8:9], v[142:143], v[16:17]
	v_pk_fma_f32 v[6:7], v[6:7], v[144:145], v[14:15]
	v_pk_fma_f32 v[4:5], v[2:3], v[148:149], v[10:11]
	v_cvt_pk_bf16_f32 v2, v6, v7
	v_cvt_pk_bf16_f32 v3, v8, v9
	v_cvt_pk_bf16_f32 v4, v4, v5
	v_cvt_pk_bf16_f32 v5, v12, v13
	global_store_dwordx4 v[18:19], v[2:5], off offset:2304
	s_cbranch_vccz .LBB0_389
	s_waitcnt vmcnt(0)
	s_cmpk_gt_u32 s30, 0xff
	s_cbranch_scc1 .LBB0_404
	s_barrier

.LBB0_1205:
	s_ashr_i32 s21, s20, 31
	s_lshl_b64 s[26:27], s[20:21], 17
	s_add_u32 s26, s36, s26
	s_addc_u32 s27, s37, s27
	s_and_b64 s[6:7], s[6:7], exec
	s_cselect_b32 s7, s27, s31
	s_cselect_b32 s6, s26, s30
	s_add_i32 s23, 0, 0x10000
	v_add_u32_e32 v173, s23, v1
	ds_read_b128 v[2:5], v173
	ds_read_b128 v[6:9], v173 offset:1024
	ds_read_b128 v[10:13], v173 offset:2048
	ds_read_b128 v[14:17], v173 offset:3072
	s_add_u32 s46, s28, 0x40080
	s_addc_u32 s47, s29, 0
	s_add_i32 s50, s3, 0xc000
	v_lshl_add_u64 v[50:51], s[46:47], 0, v[138:139]
	s_mov_b32 m0, s50
	s_add_i32 s21, s3, 0xe000
	ds_read_b128 v[18:21], v172
	ds_read_b128 v[22:25], v172 offset:1024
	ds_read_b128 v[26:29], v172 offset:2048
	ds_read_b128 v[30:33], v172 offset:3072
	ds_read_b128 v[34:37], v172 offset:4096
	ds_read_b128 v[38:41], v172 offset:5120
	ds_read_b128 v[42:45], v172 offset:6144
	ds_read_b128 v[46:49], v172 offset:7168
	global_load_lds_dwordx4 v[50:51], off
	v_lshl_add_u64 v[50:51], s[46:47], 0, v[142:143]
	s_mov_b32 m0, s21
	s_nop 0
	global_load_lds_dwordx4 v[50:51], off
	s_waitcnt lgkmcnt(8)
	s_barrier
	s_waitcnt lgkmcnt(0)
	s_waitcnt lgkmcnt(0)
	v_mfma_f32_16x16x32_bf16 v[50:53], v[2:5], v[18:21], 0
	v_mfma_f32_16x16x32_bf16 v[54:57], v[10:13], v[18:21], 0
	v_mfma_f32_16x16x32_bf16 v[58:61], v[2:5], v[26:29], 0
	v_mfma_f32_16x16x32_bf16 v[62:65], v[10:13], v[26:29], 0
	v_mfma_f32_16x16x32_bf16 v[66:69], v[2:5], v[34:37], 0
	v_mfma_f32_16x16x32_bf16 v[70:73], v[10:13], v[34:37], 0
	v_mfma_f32_16x16x32_bf16 v[74:77], v[2:5], v[42:45], 0
	v_mfma_f32_16x16x32_bf16 v[78:81], v[10:13], v[42:45], 0
	v_mfma_f32_16x16x32_bf16 v[50:53], v[6:9], v[22:25], v[50:53]
	v_mfma_f32_16x16x32_bf16 v[54:57], v[14:17], v[22:25], v[54:57]
	v_mfma_f32_16x16x32_bf16 v[58:61], v[6:9], v[30:33], v[58:61]
	v_mfma_f32_16x16x32_bf16 v[62:65], v[14:17], v[30:33], v[62:65]
	v_mfma_f32_16x16x32_bf16 v[66:69], v[6:9], v[38:41], v[66:69]
	v_mfma_f32_16x16x32_bf16 v[70:73], v[14:17], v[38:41], v[70:73]
	v_mfma_f32_16x16x32_bf16 v[74:77], v[6:9], v[46:49], v[74:77]
	v_mfma_f32_16x16x32_bf16 v[78:81], v[14:17], v[46:49], v[78:81]
	s_barrier
	s_add_i32 s48, 0, 0x14000
	v_lshl_add_u64 v[170:171], s[30:31], 0, v[140:141]
	s_mov_b64 s[52:53], 0x100
	s_add_i32 s47, s23, s38
	v_add_u32_e32 v220, s48, v1
	v_lshl_add_u64 v[98:99], v[170:171], 0, s[52:53]
	s_mov_b32 m0, s47
	v_lshl_add_u64 v[186:187], s[30:31], 0, v[144:145]
	s_add_i32 s23, s47, 0x2000
	ds_read_b128 v[82:85], v220
	ds_read_b128 v[86:89], v220 offset:1024
	ds_read_b128 v[90:93], v220 offset:2048
	ds_read_b128 v[94:97], v220 offset:3072
	global_load_lds_dwordx4 v[98:99], off
	v_lshl_add_u64 v[98:99], v[186:187], 0, s[52:53]
	s_mov_b32 m0, s23
	s_nop 0
	global_load_lds_dwordx4 v[98:99], off
	s_barrier
	s_waitcnt lgkmcnt(0)
	s_waitcnt lgkmcnt(0)
	v_mfma_f32_16x16x32_bf16 v[98:101], v[82:85], v[18:21], 0
	v_mfma_f32_16x16x32_bf16 v[18:21], v[90:93], v[18:21], 0
	v_mfma_f32_16x16x32_bf16 v[98:101], v[86:89], v[22:25], v[98:101]
	v_mfma_f32_16x16x32_bf16 v[18:21], v[94:97], v[22:25], v[18:21]
	v_mfma_f32_16x16x32_bf16 v[22:25], v[82:85], v[26:29], 0
	v_mfma_f32_16x16x32_bf16 v[26:29], v[90:93], v[26:29], 0
	v_mfma_f32_16x16x32_bf16 v[22:25], v[86:89], v[30:33], v[22:25]
	v_mfma_f32_16x16x32_bf16 v[26:29], v[94:97], v[30:33], v[26:29]
	v_mfma_f32_16x16x32_bf16 v[30:33], v[82:85], v[34:37], 0
	v_mfma_f32_16x16x32_bf16 v[34:37], v[90:93], v[34:37], 0
	v_mfma_f32_16x16x32_bf16 v[30:33], v[86:89], v[38:41], v[30:33]
	v_mfma_f32_16x16x32_bf16 v[34:37], v[94:97], v[38:41], v[34:37]
	v_mfma_f32_16x16x32_bf16 v[38:41], v[82:85], v[42:45], 0
	v_mfma_f32_16x16x32_bf16 v[42:45], v[90:93], v[42:45], 0
	v_mfma_f32_16x16x32_bf16 v[38:41], v[86:89], v[46:49], v[38:41]
	v_mfma_f32_16x16x32_bf16 v[42:45], v[94:97], v[46:49], v[42:45]
	v_lshl_add_u64 v[188:189], s[28:29], 0, v[138:139]
	s_mov_b32 m0, s3
	v_lshl_add_u64 v[130:131], v[188:189], 0, s[52:53]
	v_lshl_add_u64 v[218:219], s[28:29], 0, v[142:143]
	s_barrier
	ds_read_b128 v[46:49], v172 offset:16384
	ds_read_b128 v[102:105], v172 offset:17408
	ds_read_b128 v[106:109], v172 offset:18432
	ds_read_b128 v[110:113], v172 offset:19456
	ds_read_b128 v[114:117], v172 offset:20480
	ds_read_b128 v[118:121], v172 offset:21504
	ds_read_b128 v[122:125], v172 offset:22528
	ds_read_b128 v[126:129], v172 offset:23552
	global_load_lds_dwordx4 v[130:131], off
	v_lshl_add_u64 v[130:131], v[218:219], 0, s[52:53]
	s_mov_b32 m0, s39
	s_nop 0
	global_load_lds_dwordx4 v[130:131], off
	s_barrier
	s_waitcnt lgkmcnt(0)
	s_waitcnt lgkmcnt(0)
	v_mfma_f32_16x16x32_bf16 v[130:133], v[2:5], v[46:49], 0
	v_mfma_f32_16x16x32_bf16 v[146:149], v[2:5], v[106:109], 0
	v_mfma_f32_16x16x32_bf16 v[154:157], v[2:5], v[114:117], 0
	v_mfma_f32_16x16x32_bf16 v[2:5], v[2:5], v[122:125], 0
	v_mfma_f32_16x16x32_bf16 v[130:133], v[6:9], v[102:105], v[130:133]
	v_mfma_f32_16x16x32_bf16 v[134:137], v[10:13], v[46:49], 0
	v_mfma_f32_16x16x32_bf16 v[146:149], v[6:9], v[110:113], v[146:149]
	v_mfma_f32_16x16x32_bf16 v[150:153], v[10:13], v[106:109], 0
	v_mfma_f32_16x16x32_bf16 v[154:157], v[6:9], v[118:121], v[154:157]
	v_mfma_f32_16x16x32_bf16 v[158:161], v[10:13], v[114:117], 0
	v_mfma_f32_16x16x32_bf16 v[2:5], v[6:9], v[126:129], v[2:5]
	v_mfma_f32_16x16x32_bf16 v[6:9], v[10:13], v[122:125], 0
	v_mfma_f32_16x16x32_bf16 v[134:137], v[14:17], v[102:105], v[134:137]
	v_mfma_f32_16x16x32_bf16 v[150:153], v[14:17], v[110:113], v[150:153]
	v_mfma_f32_16x16x32_bf16 v[158:161], v[14:17], v[118:121], v[158:161]
	v_mfma_f32_16x16x32_bf16 v[6:9], v[14:17], v[126:129], v[6:9]
	s_barrier
	s_add_u32 s52, s30, 0x10100
	s_addc_u32 s53, s31, 0
	s_add_i32 s48, s48, s38
	v_lshl_add_u64 v[10:11], s[52:53], 0, v[140:141]
	s_mov_b32 m0, s48
	s_add_i32 s46, s48, 0x2000
	global_load_lds_dwordx4 v[10:11], off
	v_lshl_add_u64 v[10:11], s[52:53], 0, v[144:145]
	s_mov_b32 m0, s46
	s_nop 0
	global_load_lds_dwordx4 v[10:11], off
	s_waitcnt vmcnt(6)
	s_barrier
	v_mfma_f32_16x16x32_bf16 v[10:13], v[82:85], v[46:49], 0
	v_mfma_f32_16x16x32_bf16 v[14:17], v[90:93], v[46:49], 0
	v_mfma_f32_16x16x32_bf16 v[10:13], v[86:89], v[102:105], v[10:13]
	v_mfma_f32_16x16x32_bf16 v[14:17], v[94:97], v[102:105], v[14:17]
	v_mfma_f32_16x16x32_bf16 v[46:49], v[82:85], v[106:109], 0
	v_mfma_f32_16x16x32_bf16 v[102:105], v[90:93], v[106:109], 0
	v_mfma_f32_16x16x32_bf16 v[106:109], v[82:85], v[114:117], 0
	v_mfma_f32_16x16x32_bf16 v[82:85], v[82:85], v[122:125], 0
	v_mfma_f32_16x16x32_bf16 v[46:49], v[86:89], v[110:113], v[46:49]
	v_mfma_f32_16x16x32_bf16 v[102:105], v[94:97], v[110:113], v[102:105]
	v_mfma_f32_16x16x32_bf16 v[106:109], v[86:89], v[118:121], v[106:109]
	v_mfma_f32_16x16x32_bf16 v[110:113], v[90:93], v[114:117], 0
	v_mfma_f32_16x16x32_bf16 v[82:85], v[86:89], v[126:129], v[82:85]
	v_mfma_f32_16x16x32_bf16 v[86:89], v[90:93], v[122:125], 0
	v_mfma_f32_16x16x32_bf16 v[110:113], v[94:97], v[118:121], v[110:113]
	v_mfma_f32_16x16x32_bf16 v[86:89], v[94:97], v[126:129], v[86:89]
	s_add_i32 s51, 0, 0x18000
	v_add_u32_e32 v232, s51, v1
	s_barrier
	ds_read_b128 v[90:93], v232
	ds_read_b128 v[94:97], v232 offset:1024
	ds_read_b128 v[114:117], v232 offset:2048
	ds_read_b128 v[118:121], v232 offset:3072
	s_add_u32 s52, s28, 0x40100
	s_addc_u32 s53, s29, 0
	s_mov_b32 m0, s40
	v_lshl_add_u64 v[202:203], s[52:53], 0, v[138:139]
	ds_read_b128 v[122:125], v172 offset:32768
	ds_read_b128 v[126:129], v172 offset:33792
	ds_read_b128 v[162:165], v172 offset:34816
	ds_read_b128 v[166:169], v172 offset:35840
	ds_read_b128 v[174:177], v172 offset:36864
	ds_read_b128 v[190:193], v172 offset:37888
	ds_read_b128 v[194:197], v172 offset:38912
	ds_read_b128 v[198:201], v172 offset:39936
	global_load_lds_dwordx4 v[202:203], off
	v_lshl_add_u64 v[202:203], s[52:53], 0, v[142:143]
	s_mov_b32 m0, s41
	s_nop 0
	global_load_lds_dwordx4 v[202:203], off
	s_waitcnt lgkmcnt(8)
	s_barrier
	s_waitcnt lgkmcnt(0)
	s_waitcnt lgkmcnt(0)
	v_mfma_f32_16x16x32_bf16 v[50:53], v[90:93], v[122:125], v[50:53]
	v_mfma_f32_16x16x32_bf16 v[54:57], v[114:117], v[122:125], v[54:57]
	v_mfma_f32_16x16x32_bf16 v[58:61], v[90:93], v[162:165], v[58:61]
	v_mfma_f32_16x16x32_bf16 v[62:65], v[114:117], v[162:165], v[62:65]
	v_mfma_f32_16x16x32_bf16 v[66:69], v[90:93], v[174:177], v[66:69]
	v_mfma_f32_16x16x32_bf16 v[70:73], v[114:117], v[174:177], v[70:73]
	v_mfma_f32_16x16x32_bf16 v[74:77], v[90:93], v[194:197], v[74:77]
	v_mfma_f32_16x16x32_bf16 v[78:81], v[114:117], v[194:197], v[78:81]
	v_mfma_f32_16x16x32_bf16 v[50:53], v[94:97], v[126:129], v[50:53]
	v_mfma_f32_16x16x32_bf16 v[54:57], v[118:121], v[126:129], v[54:57]
	v_mfma_f32_16x16x32_bf16 v[58:61], v[94:97], v[166:169], v[58:61]
	v_mfma_f32_16x16x32_bf16 v[62:65], v[118:121], v[166:169], v[62:65]
	v_mfma_f32_16x16x32_bf16 v[66:69], v[94:97], v[190:193], v[66:69]
	v_mfma_f32_16x16x32_bf16 v[70:73], v[118:121], v[190:193], v[70:73]
	v_mfma_f32_16x16x32_bf16 v[74:77], v[94:97], v[198:201], v[74:77]
	v_mfma_f32_16x16x32_bf16 v[78:81], v[118:121], v[198:201], v[78:81]
	s_barrier
	s_add_i32 s54, 0, 0x1c000
	s_mov_b64 s[52:53], 0x180
	s_add_i32 s51, s51, s38
	v_add_u32_e32 v233, s54, v1
	v_lshl_add_u64 v[170:171], v[170:171], 0, s[52:53]
	s_mov_b32 m0, s51
	s_add_i32 s49, s51, 0x2000
	ds_read_b128 v[202:205], v233
	ds_read_b128 v[206:209], v233 offset:1024
	ds_read_b128 v[210:213], v233 offset:2048
	ds_read_b128 v[214:217], v233 offset:3072
	global_load_lds_dwordx4 v[170:171], off
	v_lshl_add_u64 v[170:171], v[186:187], 0, s[52:53]
	s_mov_b32 m0, s49
	s_nop 0
	global_load_lds_dwordx4 v[170:171], off
	s_barrier
	s_waitcnt lgkmcnt(0)
	s_waitcnt lgkmcnt(0)
	v_mfma_f32_16x16x32_bf16 v[98:101], v[202:205], v[122:125], v[98:101]
	v_mfma_f32_16x16x32_bf16 v[18:21], v[210:213], v[122:125], v[18:21]
	v_mfma_f32_16x16x32_bf16 v[22:25], v[202:205], v[162:165], v[22:25]
	v_mfma_f32_16x16x32_bf16 v[26:29], v[210:213], v[162:165], v[26:29]
	v_mfma_f32_16x16x32_bf16 v[30:33], v[202:205], v[174:177], v[30:33]
	v_mfma_f32_16x16x32_bf16 v[34:37], v[210:213], v[174:177], v[34:37]
	v_mfma_f32_16x16x32_bf16 v[38:41], v[202:205], v[194:197], v[38:41]
	v_mfma_f32_16x16x32_bf16 v[42:45], v[210:213], v[194:197], v[42:45]
	v_mfma_f32_16x16x32_bf16 v[98:101], v[206:209], v[126:129], v[98:101]
	v_mfma_f32_16x16x32_bf16 v[18:21], v[214:217], v[126:129], v[18:21]
	v_mfma_f32_16x16x32_bf16 v[22:25], v[206:209], v[166:169], v[22:25]
	v_mfma_f32_16x16x32_bf16 v[26:29], v[214:217], v[166:169], v[26:29]
	v_mfma_f32_16x16x32_bf16 v[30:33], v[206:209], v[190:193], v[30:33]
	v_mfma_f32_16x16x32_bf16 v[34:37], v[214:217], v[190:193], v[34:37]
	v_mfma_f32_16x16x32_bf16 v[38:41], v[206:209], v[198:201], v[38:41]
	v_mfma_f32_16x16x32_bf16 v[42:45], v[214:217], v[198:201], v[42:45]
	s_mov_b32 m0, s42
	v_lshl_add_u64 v[170:171], v[188:189], 0, s[52:53]
	s_barrier
	ds_read_b128 v[122:125], v172 offset:49152
	ds_read_b128 v[126:129], v172 offset:50176
	ds_read_b128 v[162:165], v172 offset:51200
	ds_read_b128 v[166:169], v172 offset:52224
	ds_read_b128 v[174:177], v172 offset:53248
	ds_read_b128 v[190:193], v172 offset:54272
	ds_read_b128 v[194:197], v172 offset:55296
	ds_read_b128 v[198:201], v172 offset:56320
	global_load_lds_dwordx4 v[170:171], off
	v_lshl_add_u64 v[170:171], v[218:219], 0, s[52:53]
	s_mov_b32 m0, s43
	s_nop 0
	global_load_lds_dwordx4 v[170:171], off
	s_barrier
	s_waitcnt lgkmcnt(0)
	s_waitcnt lgkmcnt(0)
	v_mfma_f32_16x16x32_bf16 v[130:133], v[90:93], v[122:125], v[130:133]
	v_mfma_f32_16x16x32_bf16 v[134:137], v[114:117], v[122:125], v[134:137]
	v_mfma_f32_16x16x32_bf16 v[146:149], v[90:93], v[162:165], v[146:149]
	v_mfma_f32_16x16x32_bf16 v[150:153], v[114:117], v[162:165], v[150:153]
	v_mfma_f32_16x16x32_bf16 v[154:157], v[90:93], v[174:177], v[154:157]
	v_mfma_f32_16x16x32_bf16 v[158:161], v[114:117], v[174:177], v[158:161]
	v_mfma_f32_16x16x32_bf16 v[2:5], v[90:93], v[194:197], v[2:5]
	v_mfma_f32_16x16x32_bf16 v[6:9], v[114:117], v[194:197], v[6:9]
	v_mfma_f32_16x16x32_bf16 v[130:133], v[94:97], v[126:129], v[130:133]
	v_mfma_f32_16x16x32_bf16 v[134:137], v[118:121], v[126:129], v[134:137]
	v_mfma_f32_16x16x32_bf16 v[146:149], v[94:97], v[166:169], v[146:149]
	v_mfma_f32_16x16x32_bf16 v[150:153], v[118:121], v[166:169], v[150:153]
	v_mfma_f32_16x16x32_bf16 v[154:157], v[94:97], v[190:193], v[154:157]
	v_mfma_f32_16x16x32_bf16 v[158:161], v[118:121], v[190:193], v[158:161]
	v_mfma_f32_16x16x32_bf16 v[2:5], v[94:97], v[198:201], v[2:5]
	v_mfma_f32_16x16x32_bf16 v[6:9], v[118:121], v[198:201], v[6:9]
	s_barrier
	s_add_u32 s52, s30, 0x10180
	s_addc_u32 s53, s31, 0
	s_add_i32 s31, s54, s38
	v_lshl_add_u64 v[90:91], s[52:53], 0, v[140:141]
	s_mov_b32 m0, s31
	s_add_i32 s30, s31, 0x2000
	global_load_lds_dwordx4 v[90:91], off
	v_lshl_add_u64 v[90:91], s[52:53], 0, v[144:145]
	s_mov_b32 m0, s30
	s_nop 0
	global_load_lds_dwordx4 v[90:91], off
	s_waitcnt vmcnt(6)
	s_barrier
	v_mfma_f32_16x16x32_bf16 v[10:13], v[202:205], v[122:125], v[10:13]
	v_mfma_f32_16x16x32_bf16 v[14:17], v[210:213], v[122:125], v[14:17]
	v_mfma_f32_16x16x32_bf16 v[46:49], v[202:205], v[162:165], v[46:49]
	v_mfma_f32_16x16x32_bf16 v[90:93], v[210:213], v[162:165], v[102:105]
	v_mfma_f32_16x16x32_bf16 v[94:97], v[202:205], v[174:177], v[106:109]
	v_mfma_f32_16x16x32_bf16 v[102:105], v[210:213], v[174:177], v[110:113]
	v_mfma_f32_16x16x32_bf16 v[82:85], v[202:205], v[194:197], v[82:85]
	v_mfma_f32_16x16x32_bf16 v[86:89], v[210:213], v[194:197], v[86:89]
	v_mfma_f32_16x16x32_bf16 v[10:13], v[206:209], v[126:129], v[10:13]
	v_mfma_f32_16x16x32_bf16 v[14:17], v[214:217], v[126:129], v[14:17]
	v_mfma_f32_16x16x32_bf16 v[46:49], v[206:209], v[166:169], v[46:49]
	v_mfma_f32_16x16x32_bf16 v[90:93], v[214:217], v[166:169], v[90:93]
	v_mfma_f32_16x16x32_bf16 v[94:97], v[206:209], v[190:193], v[94:97]
	v_mfma_f32_16x16x32_bf16 v[102:105], v[214:217], v[190:193], v[102:105]
	v_mfma_f32_16x16x32_bf16 v[82:85], v[206:209], v[198:201], v[82:85]
	v_mfma_f32_16x16x32_bf16 v[86:89], v[214:217], v[198:201], v[86:89]
	s_barrier
	ds_read_b128 v[106:109], v173
	ds_read_b128 v[110:113], v173 offset:1024
	ds_read_b128 v[114:117], v173 offset:2048
	ds_read_b128 v[118:121], v173 offset:3072
	s_add_u32 s28, s28, 0x40180
	s_addc_u32 s29, s29, 0
	s_mov_b32 m0, s50
	v_lshl_add_u64 v[170:171], s[28:29], 0, v[138:139]
	ds_read_b128 v[122:125], v172
	ds_read_b128 v[126:129], v172 offset:1024
	ds_read_b128 v[162:165], v172 offset:2048
	ds_read_b128 v[166:169], v172 offset:3072
	ds_read_b128 v[174:177], v172 offset:4096
	ds_read_b128 v[190:193], v172 offset:5120
	ds_read_b128 v[194:197], v172 offset:6144
	ds_read_b128 v[198:201], v172 offset:7168
	global_load_lds_dwordx4 v[170:171], off
	v_lshl_add_u64 v[170:171], s[28:29], 0, v[142:143]
	s_mov_b32 m0, s21
	s_nop 0
	global_load_lds_dwordx4 v[170:171], off
	s_waitcnt lgkmcnt(8)
	s_barrier
	s_waitcnt lgkmcnt(0)
	s_waitcnt lgkmcnt(0)
	v_mfma_f32_16x16x32_bf16 v[58:61], v[106:109], v[162:165], v[58:61]
	v_mfma_f32_16x16x32_bf16 v[202:205], v[110:113], v[166:169], v[58:61]
	v_mfma_f32_16x16x32_bf16 v[58:61], v[114:117], v[162:165], v[62:65]
	v_mfma_f32_16x16x32_bf16 v[62:65], v[118:121], v[166:169], v[58:61]
	v_mfma_f32_16x16x32_bf16 v[58:61], v[106:109], v[174:177], v[66:69]
	v_mfma_f32_16x16x32_bf16 v[66:69], v[110:113], v[190:193], v[58:61]
	v_mfma_f32_16x16x32_bf16 v[58:61], v[114:117], v[174:177], v[70:73]
	v_mfma_f32_16x16x32_bf16 v[70:73], v[118:121], v[190:193], v[58:61]
	v_mfma_f32_16x16x32_bf16 v[58:61], v[106:109], v[194:197], v[74:77]
	v_mfma_f32_16x16x32_bf16 v[50:53], v[106:109], v[122:125], v[50:53]
	v_mfma_f32_16x16x32_bf16 v[54:57], v[114:117], v[122:125], v[54:57]
	v_mfma_f32_16x16x32_bf16 v[74:77], v[110:113], v[198:201], v[58:61]
	v_mfma_f32_16x16x32_bf16 v[58:61], v[114:117], v[194:197], v[78:81]
	v_mfma_f32_16x16x32_bf16 v[50:53], v[110:113], v[126:129], v[50:53]
	v_mfma_f32_16x16x32_bf16 v[54:57], v[118:121], v[126:129], v[54:57]
	v_mfma_f32_16x16x32_bf16 v[78:81], v[118:121], v[198:201], v[58:61]
	s_barrier
	s_mov_b32 m0, s47
	v_lshl_add_u64 v[170:171], s[6:7], 0, v[140:141]
	s_nop 0
	ds_read_b128 v[58:61], v220
	ds_read_b128 v[206:209], v220 offset:1024
	ds_read_b128 v[210:213], v220 offset:2048
	ds_read_b128 v[214:217], v220 offset:3072
	global_load_lds_dwordx4 v[170:171], off
	v_lshl_add_u64 v[230:231], s[6:7], 0, v[144:145]
	s_mov_b32 m0, s23
	s_nop 0
	global_load_lds_dwordx4 v[230:231], off
	s_barrier
	s_waitcnt lgkmcnt(0)
	s_waitcnt lgkmcnt(0)
	v_mfma_f32_16x16x32_bf16 v[34:37], v[210:213], v[174:177], v[34:37]
	v_mfma_f32_16x16x32_bf16 v[22:25], v[58:61], v[162:165], v[22:25]
	v_mfma_f32_16x16x32_bf16 v[26:29], v[210:213], v[162:165], v[26:29]
	v_mfma_f32_16x16x32_bf16 v[162:165], v[214:217], v[190:193], v[34:37]
	v_mfma_f32_16x16x32_bf16 v[34:37], v[58:61], v[194:197], v[38:41]
	v_mfma_f32_16x16x32_bf16 v[98:101], v[58:61], v[122:125], v[98:101]
	v_mfma_f32_16x16x32_bf16 v[18:21], v[210:213], v[122:125], v[18:21]
	v_mfma_f32_16x16x32_bf16 v[30:33], v[58:61], v[174:177], v[30:33]
	v_mfma_f32_16x16x32_bf16 v[38:41], v[206:209], v[198:201], v[34:37]
	v_mfma_f32_16x16x32_bf16 v[34:37], v[210:213], v[194:197], v[42:45]
	v_mfma_f32_16x16x32_bf16 v[98:101], v[206:209], v[126:129], v[98:101]
	v_mfma_f32_16x16x32_bf16 v[18:21], v[214:217], v[126:129], v[18:21]
	v_mfma_f32_16x16x32_bf16 v[22:25], v[206:209], v[166:169], v[22:25]
	v_mfma_f32_16x16x32_bf16 v[26:29], v[214:217], v[166:169], v[26:29]
	v_mfma_f32_16x16x32_bf16 v[30:33], v[206:209], v[190:193], v[30:33]
	v_mfma_f32_16x16x32_bf16 v[166:169], v[214:217], v[198:201], v[34:37]
	s_mov_b32 m0, s3
	v_lshl_add_u64 v[252:253], s[24:25], 0, v[138:139]
	s_barrier
	ds_read_b128 v[34:37], v172 offset:16384
	ds_read_b128 v[42:45], v172 offset:17408
	ds_read_b128 v[122:125], v172 offset:18432
	ds_read_b128 v[126:129], v172 offset:19456
	ds_read_b128 v[174:177], v172 offset:20480
	ds_read_b128 v[190:193], v172 offset:21504
	ds_read_b128 v[194:197], v172 offset:22528
	ds_read_b128 v[198:201], v172 offset:23552
	global_load_lds_dwordx4 v[252:253], off
	v_lshl_add_u64 v[246:247], s[24:25], 0, v[142:143]
	s_mov_b32 m0, s39
	s_nop 0
	global_load_lds_dwordx4 v[246:247], off
	s_barrier
	s_waitcnt lgkmcnt(0)
	s_waitcnt lgkmcnt(0)
	v_mfma_f32_16x16x32_bf16 v[130:133], v[106:109], v[34:37], v[130:133]
	v_mfma_f32_16x16x32_bf16 v[218:221], v[110:113], v[42:45], v[130:133]
	v_mfma_f32_16x16x32_bf16 v[130:133], v[114:117], v[34:37], v[134:137]
	v_mfma_f32_16x16x32_bf16 v[222:225], v[118:121], v[42:45], v[130:133]
	v_mfma_f32_16x16x32_bf16 v[130:133], v[106:109], v[122:125], v[146:149]
	v_mfma_f32_16x16x32_bf16 v[146:149], v[110:113], v[126:129], v[130:133]
	v_mfma_f32_16x16x32_bf16 v[130:133], v[114:117], v[122:125], v[150:153]
	v_mfma_f32_16x16x32_bf16 v[150:153], v[118:121], v[126:129], v[130:133]
	v_mfma_f32_16x16x32_bf16 v[130:133], v[106:109], v[174:177], v[154:157]
	v_mfma_f32_16x16x32_bf16 v[154:157], v[110:113], v[190:193], v[130:133]
	v_mfma_f32_16x16x32_bf16 v[130:133], v[114:117], v[174:177], v[158:161]
	v_mfma_f32_16x16x32_bf16 v[2:5], v[106:109], v[194:197], v[2:5]
	v_mfma_f32_16x16x32_bf16 v[6:9], v[114:117], v[194:197], v[6:9]
	v_mfma_f32_16x16x32_bf16 v[158:161], v[118:121], v[190:193], v[130:133]
	v_mfma_f32_16x16x32_bf16 v[2:5], v[110:113], v[198:201], v[2:5]
	v_mfma_f32_16x16x32_bf16 v[6:9], v[118:121], v[198:201], v[6:9]
	s_barrier
	s_add_u32 s28, s6, 0x10000
	s_addc_u32 s29, s7, 0
	s_mov_b32 m0, s48
	v_lshl_add_u64 v[106:107], s[28:29], 0, v[140:141]
	global_load_lds_dwordx4 v[106:107], off
	v_lshl_add_u64 v[106:107], s[28:29], 0, v[144:145]
	s_mov_b32 m0, s46
	s_nop 0
	global_load_lds_dwordx4 v[106:107], off
	s_waitcnt vmcnt(6)
	s_barrier
	v_mfma_f32_16x16x32_bf16 v[10:13], v[58:61], v[34:37], v[10:13]
	v_mfma_f32_16x16x32_bf16 v[226:229], v[206:209], v[42:45], v[10:13]
	v_mfma_f32_16x16x32_bf16 v[10:13], v[210:213], v[34:37], v[14:17]
	v_mfma_f32_16x16x32_bf16 v[14:17], v[214:217], v[42:45], v[10:13]
	v_mfma_f32_16x16x32_bf16 v[10:13], v[58:61], v[122:125], v[46:49]
	v_mfma_f32_16x16x32_bf16 v[248:251], v[206:209], v[126:129], v[10:13]
	v_mfma_f32_16x16x32_bf16 v[10:13], v[210:213], v[122:125], v[90:93]
	v_mfma_f32_16x16x32_bf16 v[236:239], v[214:217], v[126:129], v[10:13]
	v_mfma_f32_16x16x32_bf16 v[10:13], v[58:61], v[174:177], v[94:97]
	v_mfma_f32_16x16x32_bf16 v[186:189], v[206:209], v[190:193], v[10:13]
	v_mfma_f32_16x16x32_bf16 v[10:13], v[210:213], v[174:177], v[102:105]
	v_mfma_f32_16x16x32_bf16 v[174:177], v[214:217], v[190:193], v[10:13]
	v_mfma_f32_16x16x32_bf16 v[10:13], v[58:61], v[194:197], v[82:85]
	v_mfma_f32_16x16x32_bf16 v[190:193], v[206:209], v[198:201], v[10:13]
	v_mfma_f32_16x16x32_bf16 v[10:13], v[210:213], v[194:197], v[86:89]
	v_mfma_f32_16x16x32_bf16 v[194:197], v[214:217], v[198:201], v[10:13]
	s_barrier
	ds_read_b128 v[86:89], v232
	ds_read_b128 v[94:97], v232 offset:1024
	ds_read_b128 v[102:105], v232 offset:2048
	ds_read_b128 v[198:201], v232 offset:3072
	s_add_u32 s28, s24, 0x40000
	s_addc_u32 s29, s25, 0
	s_mov_b32 m0, s40
	v_lshl_add_u64 v[34:35], s[28:29], 0, v[138:139]
	ds_read_b128 v[10:13], v172 offset:32768
	ds_read_b128 v[46:49], v172 offset:33792
	ds_read_b128 v[82:85], v172 offset:34816
	ds_read_b128 v[90:93], v172 offset:35840
	ds_read_b128 v[110:113], v172 offset:36864
	ds_read_b128 v[206:209], v172 offset:37888
	ds_read_b128 v[210:213], v172 offset:38912
	ds_read_b128 v[214:217], v172 offset:39936
	global_load_lds_dwordx4 v[34:35], off
	v_lshl_add_u64 v[34:35], s[28:29], 0, v[142:143]
	s_mov_b32 m0, s41
	s_nop 0
	global_load_lds_dwordx4 v[34:35], off
	s_waitcnt lgkmcnt(8)
	s_barrier
	s_waitcnt lgkmcnt(0)
	s_waitcnt lgkmcnt(0)
	v_mfma_f32_16x16x32_bf16 v[34:37], v[86:89], v[10:13], v[50:53]
	v_mfma_f32_16x16x32_bf16 v[130:133], v[94:97], v[46:49], v[34:37]
	v_mfma_f32_16x16x32_bf16 v[34:37], v[102:105], v[10:13], v[54:57]
	v_mfma_f32_16x16x32_bf16 v[58:61], v[198:201], v[46:49], v[34:37]
	v_mfma_f32_16x16x32_bf16 v[34:37], v[86:89], v[82:85], v[202:205]
	v_mfma_f32_16x16x32_bf16 v[122:125], v[94:97], v[90:93], v[34:37]
	v_mfma_f32_16x16x32_bf16 v[34:37], v[102:105], v[82:85], v[62:65]
	v_mfma_f32_16x16x32_bf16 v[50:53], v[198:201], v[90:93], v[34:37]
	v_mfma_f32_16x16x32_bf16 v[34:37], v[86:89], v[110:113], v[66:69]
	v_mfma_f32_16x16x32_bf16 v[114:117], v[94:97], v[206:209], v[34:37]
	v_mfma_f32_16x16x32_bf16 v[34:37], v[102:105], v[110:113], v[70:73]
	v_mfma_f32_16x16x32_bf16 v[42:45], v[198:201], v[206:209], v[34:37]
	v_mfma_f32_16x16x32_bf16 v[34:37], v[86:89], v[210:213], v[74:77]
	v_mfma_f32_16x16x32_bf16 v[106:109], v[94:97], v[214:217], v[34:37]
	v_mfma_f32_16x16x32_bf16 v[34:37], v[102:105], v[210:213], v[78:81]
	v_mfma_f32_16x16x32_bf16 v[34:37], v[198:201], v[214:217], v[34:37]
	s_barrier
	s_mov_b32 m0, s51
	v_lshl_add_u64 v[54:55], v[170:171], 0, s[0:1]
	ds_read_b128 v[70:73], v233
	ds_read_b128 v[74:77], v233 offset:1024
	ds_read_b128 v[78:81], v233 offset:2048
	ds_read_b128 v[202:205], v233 offset:3072
	global_load_lds_dwordx4 v[54:55], off
	v_lshl_add_u64 v[54:55], v[230:231], 0, s[0:1]
	s_mov_b32 m0, s49
	s_nop 0
	global_load_lds_dwordx4 v[54:55], off
	s_barrier
	s_waitcnt lgkmcnt(0)
	s_waitcnt lgkmcnt(0)
	v_mfma_f32_16x16x32_bf16 v[54:57], v[70:73], v[10:13], v[98:101]
	v_mfma_f32_16x16x32_bf16 v[10:13], v[78:81], v[10:13], v[18:21]
	v_mfma_f32_16x16x32_bf16 v[62:65], v[202:205], v[46:49], v[10:13]
	v_mfma_f32_16x16x32_bf16 v[10:13], v[70:73], v[82:85], v[22:25]
	v_mfma_f32_16x16x32_bf16 v[126:129], v[74:77], v[90:93], v[10:13]
	v_mfma_f32_16x16x32_bf16 v[10:13], v[78:81], v[82:85], v[26:29]
	v_mfma_f32_16x16x32_bf16 v[134:137], v[74:77], v[46:49], v[54:57]
	v_mfma_f32_16x16x32_bf16 v[54:57], v[202:205], v[90:93], v[10:13]
	v_mfma_f32_16x16x32_bf16 v[10:13], v[70:73], v[110:113], v[30:33]
	v_mfma_f32_16x16x32_bf16 v[118:121], v[74:77], v[206:209], v[10:13]
	v_mfma_f32_16x16x32_bf16 v[10:13], v[78:81], v[110:113], v[162:165]
	v_mfma_f32_16x16x32_bf16 v[46:49], v[202:205], v[206:209], v[10:13]
	v_mfma_f32_16x16x32_bf16 v[10:13], v[70:73], v[210:213], v[38:41]
	v_mfma_f32_16x16x32_bf16 v[110:113], v[74:77], v[214:217], v[10:13]
	v_mfma_f32_16x16x32_bf16 v[10:13], v[78:81], v[210:213], v[166:169]
	v_mfma_f32_16x16x32_bf16 v[38:41], v[202:205], v[214:217], v[10:13]
	s_mov_b32 m0, s42
	s_nop 4
	v_lshl_add_u64 v[10:11], v[252:253], 0, s[0:1]
	s_barrier
	ds_read_b128 v[22:25], v172 offset:49152
	ds_read_b128 v[30:33], v172 offset:50176
	ds_read_b128 v[162:165], v172 offset:51200
	ds_read_b128 v[166:169], v172 offset:52224
	ds_read_b128 v[206:209], v172 offset:53248
	ds_read_b128 v[210:213], v172 offset:54272
	ds_read_b128 v[214:217], v172 offset:55296
	ds_read_b128 v[230:233], v172 offset:56320
	global_load_lds_dwordx4 v[10:11], off
	v_lshl_add_u64 v[10:11], v[246:247], 0, s[0:1]
	s_mov_b32 m0, s43
	s_nop 0
	global_load_lds_dwordx4 v[10:11], off
	s_barrier
	s_waitcnt lgkmcnt(0)
	s_waitcnt lgkmcnt(0)
	v_mfma_f32_16x16x32_bf16 v[10:13], v[86:89], v[22:25], v[218:221]
	v_mfma_f32_16x16x32_bf16 v[98:101], v[94:97], v[30:33], v[10:13]
	v_mfma_f32_16x16x32_bf16 v[10:13], v[102:105], v[22:25], v[222:225]
	v_mfma_f32_16x16x32_bf16 v[26:29], v[198:201], v[30:33], v[10:13]
	v_mfma_f32_16x16x32_bf16 v[10:13], v[86:89], v[162:165], v[146:149]
	v_mfma_f32_16x16x32_bf16 v[90:93], v[94:97], v[166:169], v[10:13]
	v_mfma_f32_16x16x32_bf16 v[10:13], v[102:105], v[162:165], v[150:153]
	v_mfma_f32_16x16x32_bf16 v[18:21], v[198:201], v[166:169], v[10:13]
	v_mfma_f32_16x16x32_bf16 v[10:13], v[86:89], v[206:209], v[154:157]
	v_mfma_f32_16x16x32_bf16 v[2:5], v[86:89], v[214:217], v[2:5]
	v_mfma_f32_16x16x32_bf16 v[82:85], v[94:97], v[210:213], v[10:13]
	v_mfma_f32_16x16x32_bf16 v[10:13], v[102:105], v[206:209], v[158:161]
	v_mfma_f32_16x16x32_bf16 v[66:69], v[94:97], v[230:233], v[2:5]
	v_mfma_f32_16x16x32_bf16 v[2:5], v[102:105], v[214:217], v[6:9]
	v_mfma_f32_16x16x32_bf16 v[10:13], v[198:201], v[210:213], v[10:13]
	v_mfma_f32_16x16x32_bf16 v[2:5], v[198:201], v[230:233], v[2:5]
	s_barrier
	s_add_u32 s6, s6, 0x10080
	s_addc_u32 s7, s7, 0
	s_mov_b32 m0, s31
	v_lshl_add_u64 v[6:7], s[6:7], 0, v[140:141]
	global_load_lds_dwordx4 v[6:7], off
	v_lshl_add_u64 v[6:7], s[6:7], 0, v[144:145]
	s_mov_b32 m0, s30
	s_nop 0
	global_load_lds_dwordx4 v[6:7], off
	s_waitcnt vmcnt(6)
	s_barrier
	v_mfma_f32_16x16x32_bf16 v[6:9], v[70:73], v[22:25], v[226:229]
	v_mfma_f32_16x16x32_bf16 v[102:105], v[74:77], v[30:33], v[6:9]
	v_mfma_f32_16x16x32_bf16 v[6:9], v[78:81], v[22:25], v[14:17]
	v_mfma_f32_16x16x32_bf16 v[30:33], v[202:205], v[30:33], v[6:9]
	v_mfma_f32_16x16x32_bf16 v[6:9], v[70:73], v[162:165], v[248:251]
	v_mfma_f32_16x16x32_bf16 v[94:97], v[74:77], v[166:169], v[6:9]
	v_mfma_f32_16x16x32_bf16 v[6:9], v[78:81], v[162:165], v[236:239]
	v_mfma_f32_16x16x32_bf16 v[22:25], v[202:205], v[166:169], v[6:9]
	v_mfma_f32_16x16x32_bf16 v[6:9], v[70:73], v[206:209], v[186:189]
	v_mfma_f32_16x16x32_bf16 v[86:89], v[74:77], v[210:213], v[6:9]
	v_mfma_f32_16x16x32_bf16 v[6:9], v[78:81], v[206:209], v[174:177]
	v_mfma_f32_16x16x32_bf16 v[14:17], v[202:205], v[210:213], v[6:9]
	v_mfma_f32_16x16x32_bf16 v[6:9], v[70:73], v[214:217], v[190:193]
	v_mfma_f32_16x16x32_bf16 v[70:73], v[74:77], v[230:233], v[6:9]
	v_mfma_f32_16x16x32_bf16 v[6:9], v[78:81], v[214:217], v[194:197]
	v_mfma_f32_16x16x32_bf16 v[6:9], v[202:205], v[230:233], v[6:9]
	v_mov_b32_e32 v74, v178
	s_barrier
	s_add_i32 s45, s45, s34
	v_ashrrev_i32_e32 v75, 2, v74
	v_and_b32_e32 v75, 0xffffffc0, v75
	v_lshl_add_u32 v75, s2, 8, v75
	v_and_or_b32 v148, v74, 15, v75
	v_lshrrev_b32_e32 v74, 1, v74
	v_and_b32_e32 v74, 0x78, v74
	v_lshl_or_b32 v150, s33, 7, v74
	v_ashrrev_i32_e32 v151, 31, v150
	v_lshlrev_b64 v[146:147], 2, v[150:151]
	v_lshl_add_u64 v[154:155], s[10:11], 0, v[146:147]
	global_load_dwordx4 v[158:161], v[154:155], off
	v_lshl_add_u64 v[152:153], s[16:17], 0, v[146:147]
	v_lshl_add_u64 v[156:157], s[8:9], 0, v[146:147]
	global_load_dwordx4 v[78:81], v[152:153], off
	global_load_dwordx4 v[74:77], v[156:157], off
	v_mov_b32_e32 v166, v148
	s_mov_b32 s2, 0xc1000000
	v_ashrrev_i32_e32 v167, 31, v166
	s_mov_b32 s33, s20
	s_mov_b64 s[30:31], s[26:27]
	s_mov_b64 s[28:29], s[24:25]
	s_waitcnt vmcnt(0)
	v_max_f32_e64 v146, -v158, -v158
	v_max_f32_e32 v162, 0, v146
	v_mul_f32_e64 v146, |v158|, s72
	v_exp_f32_e32 v146, v146
	v_add_f32_e32 v130, v130, v78
	v_add_f32_e32 v131, v131, v79
	v_mul_f32_e32 v130, 0xbfb8aa3b, v130
	v_add_f32_e32 v146, 1.0, v146
	v_cmp_gt_f32_e32 vcc, s71, v146
	v_mul_f32_e32 v131, 0xbfb8aa3b, v131
	v_exp_f32_e32 v130, v130
	v_cndmask_b32_e64 v147, 0, 32, vcc
	v_ldexp_f32 v146, v146, v147
	v_log_f32_e32 v146, v146
	v_exp_f32_e32 v131, v131
	v_add_f32_e32 v130, 1.0, v130
	v_rcp_f32_e32 v170, v130
	v_mul_f32_e32 v147, 0x3f317217, v146
	v_fma_f32 v147, v146, s73, -v147
	v_fmac_f32_e32 v147, 0x3377d1cf, v146
	v_fmac_f32_e32 v147, 0x3f317217, v146
	v_cmp_lt_f32_e64 s[6:7], |v146|, s74
	v_add_f32_e32 v131, 1.0, v131
	v_rcp_f32_e32 v171, v131
	v_cndmask_b32_e64 v146, v146, v147, s[6:7]
	v_cndmask_b32_e32 v147, 0, v243, vcc
	v_sub_f32_e32 v164, v146, v147
	v_max_f32_e64 v146, -v159, -v159
	v_max_f32_e32 v163, 0, v146
	v_mul_f32_e64 v146, |v159|, s72
	v_exp_f32_e32 v146, v146
	v_add_f32_e32 v130, v134, v74
	v_add_f32_e32 v131, v135, v75
	v_mul_f32_e32 v130, 0xbfb8aa3b, v130
	v_add_f32_e32 v146, 1.0, v146
	v_cmp_gt_f32_e32 vcc, s71, v146
	v_mul_f32_e32 v131, 0xbfb8aa3b, v131
	v_exp_f32_e32 v130, v130
	v_cndmask_b32_e64 v147, 0, 32, vcc
	v_ldexp_f32 v146, v146, v147
	v_log_f32_e32 v146, v146
	v_exp_f32_e32 v131, v131
	v_add_f32_e32 v130, 1.0, v130
	v_rcp_f32_e32 v130, v130
	v_mul_f32_e32 v147, 0x3f317217, v146
	v_fma_f32 v147, v146, s73, -v147
	v_fmac_f32_e32 v147, 0x3377d1cf, v146
	v_fmac_f32_e32 v147, 0x3f317217, v146
	v_cmp_lt_f32_e64 s[6:7], |v146|, s74
	v_add_f32_e32 v131, 1.0, v131
	v_rcp_f32_e32 v131, v131
	v_cndmask_b32_e64 v146, v146, v147, s[6:7]
	v_cndmask_b32_e32 v147, 0, v243, vcc
	v_sub_f32_e32 v165, v146, v147
	v_max_f32_e64 v146, -v160, -v160
	v_max_f32_e32 v158, 0, v146
	v_mul_f32_e64 v146, |v160|, s72
	v_exp_f32_e32 v146, v146
	v_pk_add_f32 v[134:135], v[162:163], v[164:165]
	v_add_f32_e32 v122, v122, v78
	v_pk_mul_f32 v[134:135], v[134:135], s[2:3] op_sel_hi:[1,0]
	v_add_f32_e32 v146, 1.0, v146
	v_cmp_gt_f32_e32 vcc, s71, v146
	v_pk_mul_f32 v[162:163], v[170:171], v[134:135]
	v_add_f32_e32 v123, v123, v79
	v_cndmask_b32_e64 v147, 0, 32, vcc
	v_ldexp_f32 v146, v146, v147
	v_log_f32_e32 v146, v146
	v_add_f32_e32 v149, v162, v162
	v_mul_f32_e32 v149, 0x3fb8aa3b, v149
	v_exp_f32_e32 v149, v149
	v_mul_f32_e32 v147, 0x3f317217, v146
	v_fma_f32 v147, v146, s73, -v147
	v_fmac_f32_e32 v147, 0x3377d1cf, v146
	v_fmac_f32_e32 v147, 0x3f317217, v146
	v_cmp_lt_f32_e64 s[6:7], |v146|, s74
	v_sub_f32_e32 v149, 1.0, v149
	v_max_f32_e32 v149, 0, v149
	v_cndmask_b32_e64 v146, v146, v147, s[6:7]
	v_cndmask_b32_e32 v147, 0, v243, vcc
	v_sub_f32_e32 v160, v146, v147
	v_max_f32_e64 v146, -v161, -v161
	v_max_f32_e32 v159, 0, v146
	v_mul_f32_e64 v146, |v161|, s72
	v_exp_f32_e32 v146, v146
	v_sqrt_f32_e32 v164, v149
	v_add_f32_e32 v149, v163, v163
	v_mul_f32_e32 v149, 0x3fb8aa3b, v149
	v_add_f32_e32 v146, 1.0, v146
	v_cmp_gt_f32_e32 vcc, s71, v146
	v_exp_f32_e32 v149, v149
	v_mul_f32_e32 v122, 0xbfb8aa3b, v122
	v_cndmask_b32_e64 v147, 0, 32, vcc
	v_ldexp_f32 v146, v146, v147
	v_log_f32_e32 v146, v146
	v_sub_f32_e32 v149, 1.0, v149
	v_max_f32_e32 v149, 0, v149
	v_sqrt_f32_e32 v165, v149
	v_mul_f32_e32 v147, 0x3f317217, v146
	v_fma_f32 v147, v146, s73, -v147
	v_fmac_f32_e32 v147, 0x3377d1cf, v146
	v_fmac_f32_e32 v147, 0x3f317217, v146
	v_cmp_lt_f32_e64 s[6:7], |v146|, s74
	v_pk_mul_f32 v[130:131], v[130:131], v[164:165]
	v_mul_f32_e32 v123, 0xbfb8aa3b, v123
	v_cndmask_b32_e64 v146, v146, v147, s[6:7]
	v_cndmask_b32_e32 v147, 0, v243, vcc
	v_sub_f32_e32 v161, v146, v147
	v_lshlrev_b64 v[146:147], 11, v[166:167]
	v_lshl_add_u64 v[168:169], s[14:15], 0, v[146:147]
	v_lshlrev_b64 v[146:147], 1, v[150:151]
	v_lshl_add_u64 v[168:169], v[168:169], 0, v[146:147]
	v_mov_b32_e32 v230, v168
	v_mov_b32_e32 v231, v169
	v_mov_b32_e32 v232, 0x8000
	v_mov_b32_e32 v233, 0
	global_load_dwordx2 v[174:175], v[230:231], off
	global_load_dwordx2 v[202:203], v[230:231], off offset:8
	v_lshl_add_u64 v[230:231], v[230:231], 0, v[232:233]
	global_load_dwordx2 v[176:177], v[230:231], off
	global_load_dwordx2 v[204:205], v[230:231], off offset:8
	v_lshl_add_u64 v[230:231], v[230:231], 0, v[232:233]
	global_load_dwordx2 v[190:191], v[230:231], off
	global_load_dwordx2 v[206:207], v[230:231], off offset:8
	v_lshl_add_u64 v[230:231], v[230:231], 0, v[232:233]
	global_load_dwordx2 v[192:193], v[230:231], off
	global_load_dwordx2 v[208:209], v[230:231], off offset:8
	v_mov_b32_e32 v232, 0x28000
	v_lshl_add_u64 v[230:231], v[230:231], 0, v[232:233]
	v_mov_b32_e32 v232, 0x8000
	global_load_dwordx2 v[194:195], v[230:231], off
	global_load_dwordx2 v[210:211], v[230:231], off offset:8
	v_lshl_add_u64 v[230:231], v[230:231], 0, v[232:233]
	global_load_dwordx2 v[196:197], v[230:231], off
	global_load_dwordx2 v[212:213], v[230:231], off offset:8
	v_lshl_add_u64 v[230:231], v[230:231], 0, v[232:233]
	global_load_dwordx2 v[198:199], v[230:231], off
	global_load_dwordx2 v[214:215], v[230:231], off offset:8
	v_lshl_add_u64 v[230:231], v[230:231], 0, v[232:233]
	global_load_dwordx2 v[200:201], v[230:231], off
	global_load_dwordx2 v[216:217], v[230:231], off offset:8
	v_exp_f32_e32 v122, v122
	v_exp_f32_e32 v123, v123
	v_add_f32_e32 v126, v126, v74
	v_add_f32_e32 v127, v127, v75
	v_add_f32_e32 v122, 1.0, v122
	v_add_f32_e32 v123, 1.0, v123
	v_rcp_f32_e32 v122, v122
	v_rcp_f32_e32 v123, v123
	v_mul_f32_e32 v126, 0xbfb8aa3b, v126
	v_mul_f32_e32 v127, 0xbfb8aa3b, v127
	v_exp_f32_e32 v126, v126
	v_exp_f32_e32 v127, v127
	v_add_f32_e32 v114, v114, v78
	v_add_f32_e32 v115, v115, v79
	v_add_f32_e32 v126, 1.0, v126
	v_add_f32_e32 v127, 1.0, v127
	v_rcp_f32_e32 v126, v126
	v_rcp_f32_e32 v127, v127
	v_mul_f32_e32 v114, 0xbfb8aa3b, v114
	v_mul_f32_e32 v115, 0xbfb8aa3b, v115
	v_exp_f32_e32 v114, v114
	v_exp_f32_e32 v115, v115
	v_add_f32_e32 v118, v118, v74
	v_add_f32_e32 v119, v119, v75
	v_add_f32_e32 v114, 1.0, v114
	v_add_f32_e32 v115, 1.0, v115
	v_rcp_f32_e32 v114, v114
	v_rcp_f32_e32 v115, v115
	v_mul_f32_e32 v118, 0xbfb8aa3b, v118
	v_mul_f32_e32 v119, 0xbfb8aa3b, v119
	v_exp_f32_e32 v118, v118
	v_exp_f32_e32 v119, v119
	v_add_f32_e32 v106, v106, v78
	v_add_f32_e32 v107, v107, v79
	v_add_f32_e32 v118, 1.0, v118
	v_add_f32_e32 v119, 1.0, v119
	v_rcp_f32_e32 v118, v118
	v_rcp_f32_e32 v119, v119
	v_mul_f32_e32 v106, 0xbfb8aa3b, v106
	v_mul_f32_e32 v107, 0xbfb8aa3b, v107
	v_exp_f32_e32 v106, v106
	v_exp_f32_e32 v107, v107
	v_add_f32_e32 v110, v110, v74
	v_add_f32_e32 v111, v111, v75
	v_add_f32_e32 v106, 1.0, v106
	v_add_f32_e32 v107, 1.0, v107
	v_rcp_f32_e32 v106, v106
	v_rcp_f32_e32 v107, v107
	v_mul_f32_e32 v110, 0xbfb8aa3b, v110
	v_mul_f32_e32 v111, 0xbfb8aa3b, v111
	v_exp_f32_e32 v110, v110
	v_exp_f32_e32 v111, v111
	v_add_f32_e32 v98, v98, v78
	v_add_f32_e32 v99, v99, v79
	v_add_f32_e32 v110, 1.0, v110
	v_add_f32_e32 v111, 1.0, v111
	v_rcp_f32_e32 v110, v110
	v_rcp_f32_e32 v111, v111
	v_mul_f32_e32 v98, 0xbfb8aa3b, v98
	v_mul_f32_e32 v99, 0xbfb8aa3b, v99
	v_exp_f32_e32 v98, v98
	v_exp_f32_e32 v99, v99
	v_add_f32_e32 v102, v102, v74
	v_add_f32_e32 v103, v103, v75
	v_add_f32_e32 v98, 1.0, v98
	v_add_f32_e32 v99, 1.0, v99
	v_rcp_f32_e32 v98, v98
	v_rcp_f32_e32 v99, v99
	v_mul_f32_e32 v102, 0xbfb8aa3b, v102
	v_mul_f32_e32 v103, 0xbfb8aa3b, v103
	v_exp_f32_e32 v102, v102
	v_exp_f32_e32 v103, v103
	v_add_f32_e32 v90, v90, v78
	v_add_f32_e32 v91, v91, v79
	v_add_f32_e32 v102, 1.0, v102
	v_add_f32_e32 v103, 1.0, v103
	v_rcp_f32_e32 v102, v102
	v_rcp_f32_e32 v103, v103
	v_mul_f32_e32 v90, 0xbfb8aa3b, v90
	s_waitcnt vmcnt(0)
	v_mov_b32_e32 v168, v174
	v_mov_b32_e32 v169, v175
	v_lshlrev_b32_e32 v170, 16, v168
	v_and_b32_e32 v171, 0xffff0000, v168
	v_pk_mul_f32 v[164:165], v[130:131], v[170:171]
	v_add_f32_e32 v131, v136, v76
	v_mul_f32_e32 v131, 0xbfb8aa3b, v131
	v_exp_f32_e32 v131, v131
	v_add_f32_e32 v130, v132, v80
	v_mul_f32_e32 v130, 0xbfb8aa3b, v130
	v_exp_f32_e32 v130, v130
	v_add_f32_e32 v131, 1.0, v131
	v_rcp_f32_e32 v136, v131
	v_add_f32_e32 v131, v133, v81
	v_mul_f32_e32 v131, 0xbfb8aa3b, v131
	v_exp_f32_e32 v131, v131
	v_add_f32_e32 v132, v137, v77
	v_mul_f32_e32 v132, 0xbfb8aa3b, v132
	v_exp_f32_e32 v132, v132
	v_add_f32_e32 v130, 1.0, v130
	v_add_f32_e32 v131, 1.0, v131
	v_rcp_f32_e32 v130, v130
	v_rcp_f32_e32 v131, v131
	v_add_f32_e32 v132, 1.0, v132
	v_rcp_f32_e32 v137, v132
	v_pk_add_f32 v[132:133], v[158:159], v[160:161]
	v_lshlrev_b32_e32 v160, 16, v169
	v_pk_mul_f32 v[132:133], v[132:133], s[2:3] op_sel_hi:[1,0]
	v_and_b32_e32 v161, 0xffff0000, v169
	v_pk_mul_f32 v[130:131], v[130:131], v[132:133]
	v_mul_f32_e32 v91, 0xbfb8aa3b, v91
	v_add_f32_e32 v149, v130, v130
	v_mul_f32_e32 v149, 0x3fb8aa3b, v149
	v_exp_f32_e32 v149, v149
	v_exp_f32_e32 v90, v90
	v_exp_f32_e32 v91, v91
	v_add_f32_e32 v94, v94, v74
	v_sub_f32_e32 v149, 1.0, v149
	v_max_f32_e32 v149, 0, v149
	v_sqrt_f32_e32 v158, v149
	v_add_f32_e32 v149, v131, v131
	v_mul_f32_e32 v149, 0x3fb8aa3b, v149
	v_exp_f32_e32 v149, v149
	v_add_f32_e32 v90, 1.0, v90
	v_add_f32_e32 v91, 1.0, v91
	v_rcp_f32_e32 v90, v90
	v_sub_f32_e32 v149, 1.0, v149
	v_max_f32_e32 v149, 0, v149
	v_sqrt_f32_e32 v159, v149
	v_rcp_f32_e32 v91, v91
	v_add_f32_e32 v95, v95, v75
	v_mul_f32_e32 v94, 0xbfb8aa3b, v94
	v_pk_mul_f32 v[136:137], v[136:137], v[158:159]
	v_mul_f32_e32 v95, 0xbfb8aa3b, v95
	v_pk_mul_f32 v[158:159], v[136:137], v[160:161]
	v_cvt_pk_bf16_f32 v161, v130, v131
	v_mov_b64_e32 v[130:131], s[18:19]
	v_cvt_pk_bf16_f32 v160, v162, v163
	v_mad_i64_i32 v[162:163], s[6:7], v166, s84, v[130:131]
	v_lshl_add_u64 v[162:163], v[162:163], 0, v[146:147]
	v_add_co_u32_e32 v162, vcc, s69, v162
	v_add_u32_e32 v136, 16, v166
	s_nop 0
	v_addc_co_u32_e32 v163, vcc, 0, v163, vcc
	global_store_dwordx2 v[162:163], v[160:161], off offset:2048
	v_cvt_pk_bf16_f32 v160, v164, v165
	v_cvt_pk_bf16_f32 v161, v158, v159
	global_store_dwordx2 v[162:163], v[160:161], off
	v_pk_mul_f32 v[160:161], v[122:123], v[134:135]
	v_ashrrev_i32_e32 v137, 31, v136
	v_lshlrev_b64 v[158:159], 11, v[136:137]
	v_lshl_add_u64 v[158:159], s[14:15], 0, v[158:159]
	v_lshl_add_u64 v[158:159], v[158:159], 0, v[146:147]
	s_nop 0
	v_add_f32_e32 v122, v160, v160
	v_add_f32_e32 v123, v161, v161
	v_mul_f32_e32 v122, 0x3fb8aa3b, v122
	v_mul_f32_e32 v123, 0x3fb8aa3b, v123
	v_exp_f32_e32 v122, v122
	v_exp_f32_e32 v123, v123
	v_exp_f32_e32 v94, v94
	v_exp_f32_e32 v95, v95
	v_sub_f32_e32 v122, 1.0, v122
	v_sub_f32_e32 v123, 1.0, v123
	v_max_f32_e32 v122, 0, v122
	v_max_f32_e32 v123, 0, v123
	v_sqrt_f32_e32 v122, v122
	v_sqrt_f32_e32 v123, v123
	v_add_f32_e32 v94, 1.0, v94
	v_add_f32_e32 v95, 1.0, v95
	v_rcp_f32_e32 v94, v94
	v_pk_mul_f32 v[122:123], v[126:127], v[122:123]
	v_rcp_f32_e32 v95, v95
	v_add_f32_e32 v82, v82, v78
	v_add_f32_e32 v83, v83, v79
	v_mul_f32_e32 v82, 0xbfb8aa3b, v82
	v_mul_f32_e32 v83, 0xbfb8aa3b, v83
	v_exp_f32_e32 v82, v82
	v_exp_f32_e32 v83, v83
	v_add_f32_e32 v86, v86, v74
	v_add_f32_e32 v87, v87, v75
	v_add_f32_e32 v82, 1.0, v82
	v_add_f32_e32 v83, 1.0, v83
	v_rcp_f32_e32 v82, v82
	v_rcp_f32_e32 v83, v83
	v_mul_f32_e32 v86, 0xbfb8aa3b, v86
	v_mul_f32_e32 v87, 0xbfb8aa3b, v87
	v_exp_f32_e32 v86, v86
	v_exp_f32_e32 v87, v87
	v_add_f32_e32 v66, v66, v78
	v_add_f32_e32 v67, v67, v79
	v_add_f32_e32 v86, 1.0, v86
	v_add_f32_e32 v87, 1.0, v87
	v_rcp_f32_e32 v86, v86
	v_rcp_f32_e32 v87, v87
	v_mul_f32_e32 v66, 0xbfb8aa3b, v66
	v_mul_f32_e32 v67, 0xbfb8aa3b, v67
	v_exp_f32_e32 v66, v66
	v_exp_f32_e32 v67, v67
	v_add_f32_e32 v70, v70, v74
	v_add_f32_e32 v71, v71, v75
	v_add_f32_e32 v66, 1.0, v66
	v_add_f32_e32 v67, 1.0, v67
	v_rcp_f32_e32 v66, v66
	v_rcp_f32_e32 v67, v67
	v_add_f32_e32 v68, v68, v80
	v_add_f32_e32 v69, v69, v81
	v_mul_f32_e32 v68, 0xbfb8aa3b, v68
	v_pk_mul_f32 v[66:67], v[66:67], v[134:135]
	v_mul_f32_e32 v69, 0xbfb8aa3b, v69
	v_add_f32_e32 v74, v66, v66
	v_add_f32_e32 v75, v67, v67
	v_mul_f32_e32 v74, 0x3fb8aa3b, v74
	v_mul_f32_e32 v75, 0x3fb8aa3b, v75
	v_mul_f32_e32 v70, 0xbfb8aa3b, v70
	v_mul_f32_e32 v71, 0xbfb8aa3b, v71
	v_exp_f32_e32 v74, v74
	v_exp_f32_e32 v75, v75
	v_exp_f32_e32 v68, v68
	v_exp_f32_e32 v69, v69
	v_exp_f32_e32 v70, v70
	v_exp_f32_e32 v71, v71
	v_sub_f32_e32 v74, 1.0, v74
	v_sub_f32_e32 v75, 1.0, v75
	v_add_f32_e32 v68, 1.0, v68
	v_add_f32_e32 v69, 1.0, v69
	v_add_f32_e32 v70, 1.0, v70
	v_add_f32_e32 v71, 1.0, v71
	v_max_f32_e32 v74, 0, v74
	v_max_f32_e32 v75, 0, v75
	v_rcp_f32_e32 v68, v68
	v_rcp_f32_e32 v69, v69
	v_rcp_f32_e32 v70, v70
	s_nop 0
	v_mov_b32_e32 v158, v176
	v_mov_b32_e32 v159, v177
	v_lshlrev_b32_e32 v162, 16, v158
	v_and_b32_e32 v163, 0xffff0000, v158
	v_pk_mul_f32 v[126:127], v[122:123], v[162:163]
	v_add_f32_e32 v123, v128, v76
	v_mul_f32_e32 v123, 0xbfb8aa3b, v123
	v_exp_f32_e32 v123, v123
	v_add_f32_e32 v122, v124, v80
	v_mul_f32_e32 v122, 0xbfb8aa3b, v122
	v_exp_f32_e32 v122, v122
	v_add_f32_e32 v123, 1.0, v123
	v_rcp_f32_e32 v124, v123
	v_add_f32_e32 v123, v125, v81
	v_mul_f32_e32 v123, 0xbfb8aa3b, v123
	v_exp_f32_e32 v123, v123
	v_add_f32_e32 v122, 1.0, v122
	v_rcp_f32_e32 v122, v122
	v_add_f32_e32 v125, v129, v77
	v_add_f32_e32 v123, 1.0, v123
	v_rcp_f32_e32 v123, v123
	v_mul_f32_e32 v125, 0xbfb8aa3b, v125
	v_exp_f32_e32 v125, v125
	v_lshlrev_b32_e32 v158, 16, v159
	v_pk_mul_f32 v[128:129], v[122:123], v[132:133]
	v_and_b32_e32 v159, 0xffff0000, v159
	v_add_f32_e32 v122, v128, v128
	v_add_f32_e32 v123, v129, v129
	v_mul_f32_e32 v122, 0x3fb8aa3b, v122
	v_mul_f32_e32 v123, 0x3fb8aa3b, v123
	v_exp_f32_e32 v122, v122
	v_exp_f32_e32 v123, v123
	v_add_f32_e32 v125, 1.0, v125
	v_rcp_f32_e32 v125, v125
	v_sub_f32_e32 v122, 1.0, v122
	v_sub_f32_e32 v123, 1.0, v123
	v_max_f32_e32 v122, 0, v122
	v_max_f32_e32 v123, 0, v123
	v_sqrt_f32_e32 v122, v122
	v_sqrt_f32_e32 v123, v123
	v_cvt_pk_bf16_f32 v126, v126, v127
	v_rcp_f32_e32 v71, v71
	v_sqrt_f32_e32 v74, v74
	v_pk_mul_f32 v[122:123], v[124:125], v[122:123]
	v_sqrt_f32_e32 v75, v75
	v_pk_mul_f32 v[124:125], v[122:123], v[158:159]
	v_cvt_pk_bf16_f32 v159, v128, v129
	v_mad_i64_i32 v[128:129], s[6:7], v136, s84, v[130:131]
	v_lshl_add_u64 v[128:129], v[128:129], 0, v[146:147]
	v_add_co_u32_e32 v128, vcc, s69, v128
	v_add_u32_e32 v122, 16, v136
	v_cvt_pk_bf16_f32 v158, v160, v161
	v_addc_co_u32_e32 v129, vcc, 0, v129, vcc
	v_cvt_pk_bf16_f32 v127, v124, v125
	global_store_dwordx2 v[128:129], v[158:159], off offset:2048
	global_store_dwordx2 v[128:129], v[126:127], off
	v_pk_mul_f32 v[126:127], v[114:115], v[134:135]
	v_ashrrev_i32_e32 v123, 31, v122
	v_lshlrev_b64 v[124:125], 11, v[122:123]
	v_lshl_add_u64 v[124:125], s[14:15], 0, v[124:125]
	v_lshl_add_u64 v[124:125], v[124:125], 0, v[146:147]
	s_nop 0
	v_add_f32_e32 v114, v126, v126
	v_add_f32_e32 v115, v127, v127
	v_mul_f32_e32 v114, 0x3fb8aa3b, v114
	v_mul_f32_e32 v115, 0x3fb8aa3b, v115
	v_exp_f32_e32 v114, v114
	v_exp_f32_e32 v115, v115
	v_pk_mul_f32 v[68:69], v[68:69], v[132:133]
	v_pk_mul_f32 v[70:71], v[70:71], v[74:75]
	v_sub_f32_e32 v114, 1.0, v114
	v_sub_f32_e32 v115, 1.0, v115
	v_max_f32_e32 v114, 0, v114
	v_max_f32_e32 v115, 0, v115
	v_sqrt_f32_e32 v114, v114
	v_sqrt_f32_e32 v115, v115
	v_add_f32_e32 v74, v68, v68
	v_add_f32_e32 v75, v69, v69
	v_add_f32_e32 v72, v72, v76
	v_pk_mul_f32 v[114:115], v[118:119], v[114:115]
	v_add_f32_e32 v73, v73, v77
	v_mul_f32_e32 v74, 0x3fb8aa3b, v74
	v_mul_f32_e32 v75, 0x3fb8aa3b, v75
	v_mul_f32_e32 v72, 0xbfb8aa3b, v72
	v_mul_f32_e32 v73, 0xbfb8aa3b, v73
	v_exp_f32_e32 v74, v74
	v_exp_f32_e32 v75, v75
	v_exp_f32_e32 v72, v72
	v_exp_f32_e32 v73, v73
	v_sub_f32_e32 v74, 1.0, v74
	v_sub_f32_e32 v75, 1.0, v75
	v_add_f32_e32 v72, 1.0, v72
	v_add_f32_e32 v73, 1.0, v73
	v_max_f32_e32 v74, 0, v74
	v_max_f32_e32 v75, 0, v75
	v_rcp_f32_e32 v72, v72
	v_rcp_f32_e32 v73, v73
	v_sqrt_f32_e32 v74, v74
	v_sqrt_f32_e32 v75, v75
	v_cvt_pk_bf16_f32 v66, v66, v67
	v_cvt_pk_bf16_f32 v67, v68, v69
	v_pk_mul_f32 v[72:73], v[72:73], v[74:75]
	v_or_b32_e32 v74, 4, v150
	v_ashrrev_i32_e32 v75, 31, v74
	s_nop 0
	v_mov_b32_e32 v124, v190
	v_mov_b32_e32 v125, v191
	v_lshlrev_b32_e32 v128, 16, v124
	v_and_b32_e32 v129, 0xffff0000, v124
	v_pk_mul_f32 v[118:119], v[114:115], v[128:129]
	v_add_f32_e32 v115, v120, v76
	v_mul_f32_e32 v115, 0xbfb8aa3b, v115
	v_exp_f32_e32 v115, v115
	v_add_f32_e32 v114, v116, v80
	v_mul_f32_e32 v114, 0xbfb8aa3b, v114
	v_exp_f32_e32 v114, v114
	v_add_f32_e32 v115, 1.0, v115
	v_rcp_f32_e32 v116, v115
	v_add_f32_e32 v115, v117, v81
	v_mul_f32_e32 v115, 0xbfb8aa3b, v115
	v_exp_f32_e32 v115, v115
	v_add_f32_e32 v114, 1.0, v114
	v_rcp_f32_e32 v114, v114
	v_add_f32_e32 v117, v121, v77
	v_add_f32_e32 v115, 1.0, v115
	v_rcp_f32_e32 v115, v115
	v_mul_f32_e32 v117, 0xbfb8aa3b, v117
	v_exp_f32_e32 v117, v117
	v_lshlrev_b32_e32 v124, 16, v125
	v_pk_mul_f32 v[120:121], v[114:115], v[132:133]
	v_and_b32_e32 v125, 0xffff0000, v125
	v_add_f32_e32 v114, v120, v120
	v_add_f32_e32 v115, v121, v121
	v_mul_f32_e32 v114, 0x3fb8aa3b, v114
	v_mul_f32_e32 v115, 0x3fb8aa3b, v115
	v_exp_f32_e32 v114, v114
	v_exp_f32_e32 v115, v115
	v_add_f32_e32 v117, 1.0, v117
	v_rcp_f32_e32 v117, v117
	v_sub_f32_e32 v114, 1.0, v114
	v_sub_f32_e32 v115, 1.0, v115
	v_max_f32_e32 v114, 0, v114
	v_max_f32_e32 v115, 0, v115
	v_sqrt_f32_e32 v114, v114
	v_sqrt_f32_e32 v115, v115
	v_cvt_pk_bf16_f32 v118, v118, v119
	v_pk_mul_f32 v[114:115], v[116:117], v[114:115]
	s_nop 0
	v_pk_mul_f32 v[116:117], v[114:115], v[124:125]
	v_cvt_pk_bf16_f32 v125, v120, v121
	v_mad_i64_i32 v[120:121], s[6:7], v122, s84, v[130:131]
	v_lshl_add_u64 v[120:121], v[120:121], 0, v[146:147]
	v_add_co_u32_e32 v120, vcc, s69, v120
	v_add_u32_e32 v114, 16, v122
	v_cvt_pk_bf16_f32 v124, v126, v127
	v_addc_co_u32_e32 v121, vcc, 0, v121, vcc
	v_cvt_pk_bf16_f32 v119, v116, v117
	global_store_dwordx2 v[120:121], v[124:125], off offset:2048
	global_store_dwordx2 v[120:121], v[118:119], off
	v_pk_mul_f32 v[118:119], v[106:107], v[134:135]
	v_ashrrev_i32_e32 v115, 31, v114
	v_lshlrev_b64 v[116:117], 11, v[114:115]
	v_lshl_add_u64 v[116:117], s[14:15], 0, v[116:117]
	v_lshl_add_u64 v[116:117], v[116:117], 0, v[146:147]
	s_nop 0
	v_add_f32_e32 v106, v118, v118
	v_add_f32_e32 v107, v119, v119
	v_mul_f32_e32 v106, 0x3fb8aa3b, v106
	v_mul_f32_e32 v107, 0x3fb8aa3b, v107
	v_exp_f32_e32 v106, v106
	v_exp_f32_e32 v107, v107
	v_sub_f32_e32 v106, 1.0, v106
	v_sub_f32_e32 v107, 1.0, v107
	v_max_f32_e32 v106, 0, v106
	v_max_f32_e32 v107, 0, v107
	v_sqrt_f32_e32 v106, v106
	v_sqrt_f32_e32 v107, v107
	s_nop 0
	v_mov_b32_e32 v116, v192
	v_mov_b32_e32 v117, v193
	v_lshlrev_b32_e32 v120, 16, v116
	v_and_b32_e32 v121, 0xffff0000, v116
	v_pk_mul_f32 v[106:107], v[110:111], v[106:107]
	v_lshlrev_b32_e32 v116, 16, v117
	v_pk_mul_f32 v[110:111], v[106:107], v[120:121]
	v_add_f32_e32 v107, v112, v76
	v_mul_f32_e32 v107, 0xbfb8aa3b, v107
	v_exp_f32_e32 v107, v107
	v_add_f32_e32 v106, v108, v80
	v_mul_f32_e32 v106, 0xbfb8aa3b, v106
	v_exp_f32_e32 v106, v106
	v_add_f32_e32 v107, 1.0, v107
	v_rcp_f32_e32 v108, v107
	v_add_f32_e32 v107, v109, v81
	v_mul_f32_e32 v107, 0xbfb8aa3b, v107
	v_exp_f32_e32 v107, v107
	v_add_f32_e32 v106, 1.0, v106
	v_rcp_f32_e32 v106, v106
	v_add_f32_e32 v109, v113, v77
	v_add_f32_e32 v107, 1.0, v107
	v_rcp_f32_e32 v107, v107
	v_mul_f32_e32 v109, 0xbfb8aa3b, v109
	v_exp_f32_e32 v109, v109
	v_and_b32_e32 v117, 0xffff0000, v117
	v_pk_mul_f32 v[112:113], v[106:107], v[132:133]
	v_cvt_pk_bf16_f32 v110, v110, v111
	v_add_f32_e32 v106, v112, v112
	v_add_f32_e32 v107, v113, v113
	v_mul_f32_e32 v106, 0x3fb8aa3b, v106
	v_mul_f32_e32 v107, 0x3fb8aa3b, v107
	v_exp_f32_e32 v106, v106
	v_exp_f32_e32 v107, v107
	v_add_f32_e32 v109, 1.0, v109
	v_rcp_f32_e32 v109, v109
	v_sub_f32_e32 v106, 1.0, v106
	v_sub_f32_e32 v107, 1.0, v107
	v_max_f32_e32 v106, 0, v106
	v_max_f32_e32 v107, 0, v107
	v_sqrt_f32_e32 v106, v106
	v_sqrt_f32_e32 v107, v107
	s_nop 0
	v_pk_mul_f32 v[106:107], v[108:109], v[106:107]
	s_nop 0
	v_pk_mul_f32 v[108:109], v[106:107], v[116:117]
	v_cvt_pk_bf16_f32 v117, v112, v113
	v_mad_i64_i32 v[112:113], s[6:7], v114, s84, v[130:131]
	v_lshl_add_u64 v[112:113], v[112:113], 0, v[146:147]
	v_add_co_u32_e32 v112, vcc, s69, v112
	v_add_u32_e32 v106, 0x50, v114
	v_cvt_pk_bf16_f32 v116, v118, v119
	v_addc_co_u32_e32 v113, vcc, 0, v113, vcc
	v_cvt_pk_bf16_f32 v111, v108, v109
	global_store_dwordx2 v[112:113], v[116:117], off offset:2048
	global_store_dwordx2 v[112:113], v[110:111], off
	v_pk_mul_f32 v[110:111], v[98:99], v[134:135]
	v_ashrrev_i32_e32 v107, 31, v106
	v_lshlrev_b64 v[108:109], 11, v[106:107]
	v_lshl_add_u64 v[108:109], s[14:15], 0, v[108:109]
	v_lshl_add_u64 v[108:109], v[108:109], 0, v[146:147]
	s_nop 0
	v_add_f32_e32 v98, v110, v110
	v_add_f32_e32 v99, v111, v111
	v_mul_f32_e32 v98, 0x3fb8aa3b, v98
	v_mul_f32_e32 v99, 0x3fb8aa3b, v99
	v_exp_f32_e32 v98, v98
	v_exp_f32_e32 v99, v99
	v_sub_f32_e32 v98, 1.0, v98
	v_sub_f32_e32 v99, 1.0, v99
	v_max_f32_e32 v98, 0, v98
	v_max_f32_e32 v99, 0, v99
	v_sqrt_f32_e32 v98, v98
	v_sqrt_f32_e32 v99, v99
	s_nop 0
	v_mov_b32_e32 v108, v194
	v_mov_b32_e32 v109, v195
	v_lshlrev_b32_e32 v112, 16, v108
	v_and_b32_e32 v113, 0xffff0000, v108
	v_pk_mul_f32 v[98:99], v[102:103], v[98:99]
	v_lshlrev_b32_e32 v108, 16, v109
	v_pk_mul_f32 v[102:103], v[98:99], v[112:113]
	v_add_f32_e32 v99, v104, v76
	v_mul_f32_e32 v99, 0xbfb8aa3b, v99
	v_exp_f32_e32 v99, v99
	v_add_f32_e32 v98, v100, v80
	v_mul_f32_e32 v98, 0xbfb8aa3b, v98
	v_exp_f32_e32 v98, v98
	v_add_f32_e32 v99, 1.0, v99
	v_rcp_f32_e32 v100, v99
	v_add_f32_e32 v99, v101, v81
	v_mul_f32_e32 v99, 0xbfb8aa3b, v99
	v_exp_f32_e32 v99, v99
	v_add_f32_e32 v98, 1.0, v98
	v_rcp_f32_e32 v98, v98
	v_add_f32_e32 v101, v105, v77
	v_add_f32_e32 v99, 1.0, v99
	v_rcp_f32_e32 v99, v99
	v_mul_f32_e32 v101, 0xbfb8aa3b, v101
	v_exp_f32_e32 v101, v101
	v_and_b32_e32 v109, 0xffff0000, v109
	v_pk_mul_f32 v[104:105], v[98:99], v[132:133]
	v_cvt_pk_bf16_f32 v102, v102, v103
	v_add_f32_e32 v98, v104, v104
	v_add_f32_e32 v99, v105, v105
	v_mul_f32_e32 v98, 0x3fb8aa3b, v98
	v_mul_f32_e32 v99, 0x3fb8aa3b, v99
	v_exp_f32_e32 v98, v98
	v_exp_f32_e32 v99, v99
	v_add_f32_e32 v101, 1.0, v101
	v_rcp_f32_e32 v101, v101
	v_sub_f32_e32 v98, 1.0, v98
	v_sub_f32_e32 v99, 1.0, v99
	v_max_f32_e32 v98, 0, v98
	v_max_f32_e32 v99, 0, v99
	v_sqrt_f32_e32 v98, v98
	v_sqrt_f32_e32 v99, v99
	s_nop 0
	v_pk_mul_f32 v[98:99], v[100:101], v[98:99]
	s_nop 0
	v_pk_mul_f32 v[100:101], v[98:99], v[108:109]
	v_cvt_pk_bf16_f32 v109, v104, v105
	v_mad_i64_i32 v[104:105], s[6:7], v106, s84, v[130:131]
	v_lshl_add_u64 v[104:105], v[104:105], 0, v[146:147]
	v_add_co_u32_e32 v104, vcc, s69, v104
	v_add_u32_e32 v98, 16, v106
	v_cvt_pk_bf16_f32 v108, v110, v111
	v_addc_co_u32_e32 v105, vcc, 0, v105, vcc
	v_cvt_pk_bf16_f32 v103, v100, v101
	global_store_dwordx2 v[104:105], v[108:109], off offset:2048
	global_store_dwordx2 v[104:105], v[102:103], off
	v_pk_mul_f32 v[102:103], v[90:91], v[134:135]
	v_ashrrev_i32_e32 v99, 31, v98
	v_lshlrev_b64 v[100:101], 11, v[98:99]
	v_lshl_add_u64 v[100:101], s[14:15], 0, v[100:101]
	v_lshl_add_u64 v[100:101], v[100:101], 0, v[146:147]
	s_nop 0
	v_add_f32_e32 v90, v102, v102
	v_add_f32_e32 v91, v103, v103
	v_mul_f32_e32 v90, 0x3fb8aa3b, v90
	v_mul_f32_e32 v91, 0x3fb8aa3b, v91
	v_exp_f32_e32 v90, v90
	v_exp_f32_e32 v91, v91
	v_sub_f32_e32 v90, 1.0, v90
	v_sub_f32_e32 v91, 1.0, v91
	v_max_f32_e32 v90, 0, v90
	v_max_f32_e32 v91, 0, v91
	v_sqrt_f32_e32 v90, v90
	v_sqrt_f32_e32 v91, v91
	s_nop 0
	v_mov_b32_e32 v100, v196
	v_mov_b32_e32 v101, v197
	v_lshlrev_b32_e32 v104, 16, v100
	v_and_b32_e32 v105, 0xffff0000, v100
	v_pk_mul_f32 v[90:91], v[94:95], v[90:91]
	v_lshlrev_b32_e32 v100, 16, v101
	v_pk_mul_f32 v[94:95], v[90:91], v[104:105]
	v_add_f32_e32 v91, v96, v76
	v_mul_f32_e32 v91, 0xbfb8aa3b, v91
	v_exp_f32_e32 v91, v91
	v_add_f32_e32 v90, v92, v80
	v_mul_f32_e32 v90, 0xbfb8aa3b, v90
	v_exp_f32_e32 v90, v90
	v_add_f32_e32 v91, 1.0, v91
	v_rcp_f32_e32 v92, v91
	v_add_f32_e32 v91, v93, v81
	v_mul_f32_e32 v91, 0xbfb8aa3b, v91
	v_exp_f32_e32 v91, v91
	v_add_f32_e32 v90, 1.0, v90
	v_rcp_f32_e32 v90, v90
	v_add_f32_e32 v93, v97, v77
	v_add_f32_e32 v91, 1.0, v91
	v_rcp_f32_e32 v91, v91
	v_mul_f32_e32 v93, 0xbfb8aa3b, v93
	v_exp_f32_e32 v93, v93
	v_and_b32_e32 v101, 0xffff0000, v101
	v_pk_mul_f32 v[96:97], v[90:91], v[132:133]
	v_cvt_pk_bf16_f32 v94, v94, v95
	v_add_f32_e32 v90, v96, v96
	v_add_f32_e32 v91, v97, v97
	v_mul_f32_e32 v90, 0x3fb8aa3b, v90
	v_mul_f32_e32 v91, 0x3fb8aa3b, v91
	v_exp_f32_e32 v90, v90
	v_exp_f32_e32 v91, v91
	v_add_f32_e32 v93, 1.0, v93
	v_rcp_f32_e32 v93, v93
	v_sub_f32_e32 v90, 1.0, v90
	v_sub_f32_e32 v91, 1.0, v91
	v_max_f32_e32 v90, 0, v90
	v_max_f32_e32 v91, 0, v91
	v_sqrt_f32_e32 v90, v90
	v_sqrt_f32_e32 v91, v91
	s_nop 0
	v_pk_mul_f32 v[90:91], v[92:93], v[90:91]
	s_nop 0
	v_pk_mul_f32 v[92:93], v[90:91], v[100:101]
	v_cvt_pk_bf16_f32 v101, v96, v97
	v_mad_i64_i32 v[96:97], s[6:7], v98, s84, v[130:131]
	v_lshl_add_u64 v[96:97], v[96:97], 0, v[146:147]
	v_add_co_u32_e32 v96, vcc, s69, v96
	v_add_u32_e32 v90, 16, v98
	v_cvt_pk_bf16_f32 v100, v102, v103
	v_addc_co_u32_e32 v97, vcc, 0, v97, vcc
	v_cvt_pk_bf16_f32 v95, v92, v93
	global_store_dwordx2 v[96:97], v[100:101], off offset:2048
	global_store_dwordx2 v[96:97], v[94:95], off
	v_pk_mul_f32 v[94:95], v[82:83], v[134:135]
	v_ashrrev_i32_e32 v91, 31, v90
	v_lshlrev_b64 v[92:93], 11, v[90:91]
	v_lshl_add_u64 v[92:93], s[14:15], 0, v[92:93]
	v_lshl_add_u64 v[92:93], v[92:93], 0, v[146:147]
	s_nop 0
	v_add_f32_e32 v82, v94, v94
	v_add_f32_e32 v83, v95, v95
	v_mul_f32_e32 v82, 0x3fb8aa3b, v82
	v_mul_f32_e32 v83, 0x3fb8aa3b, v83
	v_exp_f32_e32 v82, v82
	v_exp_f32_e32 v83, v83
	v_sub_f32_e32 v82, 1.0, v82
	v_sub_f32_e32 v83, 1.0, v83
	v_max_f32_e32 v82, 0, v82
	v_max_f32_e32 v83, 0, v83
	v_sqrt_f32_e32 v82, v82
	v_sqrt_f32_e32 v83, v83
	s_nop 0
	v_mov_b32_e32 v92, v198
	v_mov_b32_e32 v93, v199
	v_lshlrev_b32_e32 v96, 16, v92
	v_and_b32_e32 v97, 0xffff0000, v92
	v_pk_mul_f32 v[82:83], v[86:87], v[82:83]
	v_lshlrev_b32_e32 v92, 16, v93
	v_pk_mul_f32 v[86:87], v[82:83], v[96:97]
	v_add_f32_e32 v83, v88, v76
	v_mul_f32_e32 v83, 0xbfb8aa3b, v83
	v_exp_f32_e32 v83, v83
	v_add_f32_e32 v82, v84, v80
	v_mul_f32_e32 v82, 0xbfb8aa3b, v82
	v_exp_f32_e32 v82, v82
	v_add_f32_e32 v83, 1.0, v83
	v_rcp_f32_e32 v84, v83
	v_add_f32_e32 v83, v85, v81
	v_mul_f32_e32 v83, 0xbfb8aa3b, v83
	v_exp_f32_e32 v83, v83
	v_add_f32_e32 v82, 1.0, v82
	v_rcp_f32_e32 v82, v82
	v_add_f32_e32 v85, v89, v77
	v_add_f32_e32 v83, 1.0, v83
	v_rcp_f32_e32 v83, v83
	v_mul_f32_e32 v85, 0xbfb8aa3b, v85
	v_exp_f32_e32 v85, v85
	v_and_b32_e32 v93, 0xffff0000, v93
	v_pk_mul_f32 v[88:89], v[82:83], v[132:133]
	v_cvt_pk_bf16_f32 v86, v86, v87
	v_add_f32_e32 v82, v88, v88
	v_add_f32_e32 v83, v89, v89
	v_mul_f32_e32 v82, 0x3fb8aa3b, v82
	v_mul_f32_e32 v83, 0x3fb8aa3b, v83
	v_exp_f32_e32 v82, v82
	v_exp_f32_e32 v83, v83
	v_add_f32_e32 v85, 1.0, v85
	v_rcp_f32_e32 v85, v85
	v_sub_f32_e32 v82, 1.0, v82
	v_sub_f32_e32 v83, 1.0, v83
	v_max_f32_e32 v82, 0, v82
	v_max_f32_e32 v83, 0, v83
	v_sqrt_f32_e32 v82, v82
	v_sqrt_f32_e32 v83, v83
	s_nop 0
	v_pk_mul_f32 v[82:83], v[84:85], v[82:83]
	s_nop 0
	v_pk_mul_f32 v[84:85], v[82:83], v[92:93]
	v_cvt_pk_bf16_f32 v93, v88, v89
	v_mad_i64_i32 v[88:89], s[6:7], v90, s84, v[130:131]
	v_lshl_add_u64 v[88:89], v[88:89], 0, v[146:147]
	v_add_co_u32_e32 v88, vcc, s69, v88
	v_add_u32_e32 v82, 16, v90
	v_cvt_pk_bf16_f32 v92, v94, v95
	v_addc_co_u32_e32 v89, vcc, 0, v89, vcc
	v_cvt_pk_bf16_f32 v87, v84, v85
	global_store_dwordx2 v[88:89], v[92:93], off offset:2048
	global_store_dwordx2 v[88:89], v[86:87], off
	s_nop 0
	v_ashrrev_i32_e32 v83, 31, v82
	v_lshlrev_b64 v[84:85], 11, v[82:83]
	v_lshl_add_u64 v[84:85], s[14:15], 0, v[84:85]
	v_lshl_add_u64 v[84:85], v[84:85], 0, v[146:147]
	s_nop 0
	v_mad_i64_i32 v[68:69], s[6:7], v82, s84, v[130:131]
	v_lshl_add_u64 v[68:69], v[68:69], 0, v[146:147]
	v_add_co_u32_e32 v68, vcc, s69, v68
	s_nop 0
	v_mov_b32_e32 v84, v200
	v_mov_b32_e32 v85, v201
	v_lshlrev_b32_e32 v78, 16, v84
	v_and_b32_e32 v79, 0xffff0000, v84
	v_lshlrev_b32_e32 v76, 16, v85
	v_and_b32_e32 v77, 0xffff0000, v85
	v_pk_mul_f32 v[70:71], v[70:71], v[78:79]
	v_pk_mul_f32 v[72:73], v[72:73], v[76:77]
	v_addc_co_u32_e32 v69, vcc, 0, v69, vcc
	global_store_dwordx2 v[68:69], v[66:67], off offset:2048
	v_cvt_pk_bf16_f32 v66, v70, v71
	v_cvt_pk_bf16_f32 v67, v72, v73
	global_store_dwordx2 v[68:69], v[66:67], off
	global_load_dwordx4 v[70:73], v[152:153], off offset:16
	s_nop 0
	global_load_dwordx4 v[66:69], v[156:157], off offset:16
	global_load_dwordx4 v[76:79], v[154:155], off offset:16
	s_waitcnt vmcnt(0)
	v_add_f32_e32 v58, v58, v70
	v_ashrrev_i32_e32 v149, 31, v148
	v_max_f32_e64 v80, -v76, -v76
	v_mul_f32_e64 v76, |v76|, s72
	v_exp_f32_e32 v76, v76
	v_mul_f32_e32 v58, 0xbfb8aa3b, v58
	v_exp_f32_e32 v58, v58
	v_max_f32_e32 v80, 0, v80
	v_add_f32_e32 v76, 1.0, v76
	v_cmp_gt_f32_e32 vcc, s71, v76
	v_add_f32_e32 v58, 1.0, v58
	v_rcp_f32_e32 v86, v58
	v_cndmask_b32_e64 v81, 0, 32, vcc
	v_ldexp_f32 v76, v76, v81
	v_log_f32_e32 v76, v76
	v_add_f32_e32 v58, v62, v66
	v_mul_f32_e32 v58, 0xbfb8aa3b, v58
	v_exp_f32_e32 v58, v58
	v_mul_f32_e32 v81, 0x3f317217, v76
	v_fma_f32 v81, v76, s73, -v81
	v_fmac_f32_e32 v81, 0x3377d1cf, v76
	v_fmac_f32_e32 v81, 0x3f317217, v76
	v_cmp_lt_f32_e64 s[6:7], |v76|, s74
	v_add_f32_e32 v58, 1.0, v58
	v_rcp_f32_e32 v62, v58
	v_cndmask_b32_e64 v76, v76, v81, s[6:7]
	v_cndmask_b32_e32 v81, 0, v243, vcc
	v_sub_f32_e32 v82, v76, v81
	v_max_f32_e64 v76, -v77, -v77
	v_max_f32_e32 v81, 0, v76
	v_mul_f32_e64 v76, |v77|, s72
	v_exp_f32_e32 v76, v76
	v_add_f32_e32 v58, v59, v71
	v_mul_f32_e32 v58, 0xbfb8aa3b, v58
	v_exp_f32_e32 v58, v58
	v_add_f32_e32 v76, 1.0, v76
	v_cmp_gt_f32_e32 vcc, s71, v76
	v_add_f32_e32 v60, v60, v72
	v_add_f32_e32 v58, 1.0, v58
	v_cndmask_b32_e64 v77, 0, 32, vcc
	v_ldexp_f32 v76, v76, v77
	v_log_f32_e32 v76, v76
	v_rcp_f32_e32 v87, v58
	v_add_f32_e32 v58, v63, v67
	v_mul_f32_e32 v58, 0xbfb8aa3b, v58
	v_mul_f32_e32 v77, 0x3f317217, v76
	v_fma_f32 v77, v76, s73, -v77
	v_fmac_f32_e32 v77, 0x3377d1cf, v76
	v_fmac_f32_e32 v77, 0x3f317217, v76
	v_cmp_lt_f32_e64 s[6:7], |v76|, s74
	v_exp_f32_e32 v58, v58
	v_mul_f32_e32 v60, 0xbfb8aa3b, v60
	v_cndmask_b32_e64 v76, v76, v77, s[6:7]
	v_cndmask_b32_e32 v77, 0, v243, vcc
	v_sub_f32_e32 v83, v76, v77
	v_mul_f32_e64 v77, |v78|, s72
	v_exp_f32_e32 v77, v77
	v_max_f32_e64 v76, -v78, -v78
	v_add_f32_e32 v58, 1.0, v58
	v_rcp_f32_e32 v63, v58
	v_add_f32_e32 v77, 1.0, v77
	v_cmp_gt_f32_e32 vcc, s71, v77
	v_pk_add_f32 v[58:59], v[80:81], v[82:83]
	v_exp_f32_e32 v60, v60
	v_cndmask_b32_e64 v78, 0, 32, vcc
	v_ldexp_f32 v77, v77, v78
	v_log_f32_e32 v77, v77
	v_pk_mul_f32 v[58:59], v[58:59], s[2:3] op_sel_hi:[1,0]
	v_add_f32_e32 v60, 1.0, v60
	v_pk_mul_f32 v[80:81], v[86:87], v[58:59]
	v_mul_f32_e32 v78, 0x3f317217, v77
	v_fma_f32 v78, v77, s73, -v78
	v_fmac_f32_e32 v78, 0x3377d1cf, v77
	v_fmac_f32_e32 v78, 0x3f317217, v77
	v_cmp_lt_f32_e64 s[6:7], |v77|, s74
	v_add_f32_e32 v82, v80, v80
	v_add_f32_e32 v83, v81, v81
	v_cndmask_b32_e64 v77, v77, v78, s[6:7]
	v_cndmask_b32_e32 v78, 0, v243, vcc
	v_sub_f32_e32 v78, v77, v78
	v_max_f32_e64 v77, -v79, -v79
	v_mul_f32_e64 v79, |v79|, s72
	v_exp_f32_e32 v79, v79
	v_mul_f32_e32 v82, 0x3fb8aa3b, v82
	v_mul_f32_e32 v83, 0x3fb8aa3b, v83
	v_exp_f32_e32 v82, v82
	v_add_f32_e32 v79, 1.0, v79
	v_cmp_gt_f32_e32 vcc, s71, v79
	v_exp_f32_e32 v83, v83
	v_sub_f32_e32 v82, 1.0, v82
	v_cndmask_b32_e64 v84, 0, 32, vcc
	v_ldexp_f32 v79, v79, v84
	v_log_f32_e32 v79, v79
	v_sub_f32_e32 v83, 1.0, v83
	v_max_f32_e32 v82, 0, v82
	v_max_f32_e32 v83, 0, v83
	v_mul_f32_e32 v84, 0x3f317217, v79
	v_fma_f32 v84, v79, s73, -v84
	v_fmac_f32_e32 v84, 0x3377d1cf, v79
	v_fmac_f32_e32 v84, 0x3f317217, v79
	v_cmp_lt_f32_e64 s[6:7], |v79|, s74
	v_sqrt_f32_e32 v82, v82
	v_sqrt_f32_e32 v83, v83
	v_cndmask_b32_e64 v79, v79, v84, s[6:7]
	v_cndmask_b32_e32 v84, 0, v243, vcc
	v_sub_f32_e32 v79, v79, v84
	v_lshlrev_b64 v[84:85], 11, v[148:149]
	v_lshl_add_u64 v[84:85], s[14:15], 0, v[84:85]
	v_lshl_add_u64 v[84:85], v[84:85], 0, v[146:147]
	s_nop 0
	v_pk_mul_f32 v[62:63], v[62:63], v[82:83]
	v_max_f32_e32 v76, 0, v76
	v_max_f32_e32 v77, 0, v77
	v_add_f32_e32 v50, v50, v70
	v_add_f32_e32 v51, v51, v71
	v_mul_f32_e32 v50, 0xbfb8aa3b, v50
	v_mul_f32_e32 v51, 0xbfb8aa3b, v51
	v_exp_f32_e32 v50, v50
	v_exp_f32_e32 v51, v51
	v_add_f32_e32 v54, v54, v66
	v_add_f32_e32 v55, v55, v67
	v_add_f32_e32 v50, 1.0, v50
	v_add_f32_e32 v51, 1.0, v51
	v_rcp_f32_e32 v50, v50
	v_rcp_f32_e32 v51, v51
	v_mul_f32_e32 v54, 0xbfb8aa3b, v54
	v_mul_f32_e32 v55, 0xbfb8aa3b, v55
	v_exp_f32_e32 v54, v54
	v_exp_f32_e32 v55, v55
	v_add_f32_e32 v42, v42, v70
	v_add_f32_e32 v43, v43, v71
	v_add_f32_e32 v54, 1.0, v54
	v_add_f32_e32 v55, 1.0, v55
	v_rcp_f32_e32 v54, v54
	v_rcp_f32_e32 v55, v55
	v_mul_f32_e32 v42, 0xbfb8aa3b, v42
	v_mul_f32_e32 v43, 0xbfb8aa3b, v43
	v_exp_f32_e32 v42, v42
	v_exp_f32_e32 v43, v43
	v_add_f32_e32 v46, v46, v66
	v_add_f32_e32 v47, v47, v67
	v_add_f32_e32 v42, 1.0, v42
	v_add_f32_e32 v43, 1.0, v43
	v_rcp_f32_e32 v42, v42
	v_rcp_f32_e32 v43, v43
	v_mul_f32_e32 v46, 0xbfb8aa3b, v46
	v_mul_f32_e32 v47, 0xbfb8aa3b, v47
	v_exp_f32_e32 v46, v46
	v_exp_f32_e32 v47, v47
	v_add_f32_e32 v34, v34, v70
	v_add_f32_e32 v35, v35, v71
	v_add_f32_e32 v46, 1.0, v46
	v_add_f32_e32 v47, 1.0, v47
	v_rcp_f32_e32 v46, v46
	v_rcp_f32_e32 v47, v47
	v_mul_f32_e32 v34, 0xbfb8aa3b, v34
	v_mul_f32_e32 v35, 0xbfb8aa3b, v35
	v_exp_f32_e32 v34, v34
	v_exp_f32_e32 v35, v35
	v_add_f32_e32 v38, v38, v66
	v_add_f32_e32 v39, v39, v67
	v_add_f32_e32 v34, 1.0, v34
	v_add_f32_e32 v35, 1.0, v35
	v_rcp_f32_e32 v34, v34
	v_rcp_f32_e32 v35, v35
	v_mul_f32_e32 v38, 0xbfb8aa3b, v38
	v_mul_f32_e32 v39, 0xbfb8aa3b, v39
	v_exp_f32_e32 v38, v38
	v_exp_f32_e32 v39, v39
	v_add_f32_e32 v26, v26, v70
	v_add_f32_e32 v27, v27, v71
	v_add_f32_e32 v38, 1.0, v38
	v_add_f32_e32 v39, 1.0, v39
	v_rcp_f32_e32 v38, v38
	v_rcp_f32_e32 v39, v39
	v_mul_f32_e32 v26, 0xbfb8aa3b, v26
	v_mul_f32_e32 v27, 0xbfb8aa3b, v27
	v_exp_f32_e32 v26, v26
	v_exp_f32_e32 v27, v27
	v_add_f32_e32 v30, v30, v66
	v_add_f32_e32 v31, v31, v67
	v_add_f32_e32 v26, 1.0, v26
	v_add_f32_e32 v27, 1.0, v27
	v_rcp_f32_e32 v26, v26
	v_rcp_f32_e32 v27, v27
	v_mul_f32_e32 v30, 0xbfb8aa3b, v30
	v_mul_f32_e32 v31, 0xbfb8aa3b, v31
	v_exp_f32_e32 v30, v30
	v_exp_f32_e32 v31, v31
	s_nop 0
	v_mov_b32_e32 v84, v202
	v_mov_b32_e32 v85, v203
	v_lshlrev_b32_e32 v86, 16, v84
	v_and_b32_e32 v87, 0xffff0000, v84
	v_pk_mul_f32 v[82:83], v[62:63], v[86:87]
	v_rcp_f32_e32 v62, v60
	v_add_f32_e32 v60, v64, v68
	v_mul_f32_e32 v60, 0xbfb8aa3b, v60
	v_exp_f32_e32 v60, v60
	v_add_f32_e32 v30, 1.0, v30
	v_add_f32_e32 v31, 1.0, v31
	v_rcp_f32_e32 v30, v30
	v_add_f32_e32 v60, 1.0, v60
	v_rcp_f32_e32 v64, v60
	v_add_f32_e32 v60, v61, v73
	v_mul_f32_e32 v60, 0xbfb8aa3b, v60
	v_exp_f32_e32 v60, v60
	v_rcp_f32_e32 v31, v31
	v_add_f32_e32 v18, v18, v70
	v_add_f32_e32 v19, v19, v71
	v_add_f32_e32 v60, 1.0, v60
	v_rcp_f32_e32 v63, v60
	v_add_f32_e32 v60, v65, v69
	v_mul_f32_e32 v60, 0xbfb8aa3b, v60
	v_exp_f32_e32 v60, v60
	v_mul_f32_e32 v18, 0xbfb8aa3b, v18
	v_mul_f32_e32 v19, 0xbfb8aa3b, v19
	v_exp_f32_e32 v18, v18
	v_add_f32_e32 v60, 1.0, v60
	v_rcp_f32_e32 v65, v60
	v_pk_add_f32 v[60:61], v[76:77], v[78:79]
	v_lshlrev_b32_e32 v78, 16, v85
	v_pk_mul_f32 v[60:61], v[60:61], s[2:3] op_sel_hi:[1,0]
	v_and_b32_e32 v79, 0xffff0000, v85
	v_pk_mul_f32 v[62:63], v[62:63], v[60:61]
	v_exp_f32_e32 v19, v19
	v_add_f32_e32 v76, v62, v62
	v_add_f32_e32 v77, v63, v63
	v_mul_f32_e32 v76, 0x3fb8aa3b, v76
	v_mul_f32_e32 v77, 0x3fb8aa3b, v77
	v_exp_f32_e32 v76, v76
	v_exp_f32_e32 v77, v77
	v_add_f32_e32 v18, 1.0, v18
	v_add_f32_e32 v19, 1.0, v19
	v_sub_f32_e32 v76, 1.0, v76
	v_sub_f32_e32 v77, 1.0, v77
	v_max_f32_e32 v76, 0, v76
	v_max_f32_e32 v77, 0, v77
	v_sqrt_f32_e32 v76, v76
	v_sqrt_f32_e32 v77, v77
	v_rcp_f32_e32 v18, v18
	v_rcp_f32_e32 v19, v19
	v_add_f32_e32 v22, v22, v66
	v_pk_mul_f32 v[64:65], v[64:65], v[76:77]
	v_add_f32_e32 v23, v23, v67
	v_pk_mul_f32 v[76:77], v[64:65], v[78:79]
	v_cvt_pk_bf16_f32 v78, v80, v81
	v_cvt_pk_bf16_f32 v79, v62, v63
	v_mad_i64_i32 v[80:81], s[6:7], v148, s84, v[130:131]
	v_lshlrev_b64 v[62:63], 1, v[74:75]
	v_lshl_add_u64 v[74:75], v[80:81], 0, v[62:63]
	v_add_co_u32_e32 v74, vcc, s69, v74
	v_add_u32_e32 v64, 16, v148
	s_nop 0
	v_addc_co_u32_e32 v75, vcc, 0, v75, vcc
	global_store_dwordx2 v[74:75], v[78:79], off offset:2048
	v_cvt_pk_bf16_f32 v78, v82, v83
	v_cvt_pk_bf16_f32 v79, v76, v77
	global_store_dwordx2 v[74:75], v[78:79], off
	v_pk_mul_f32 v[76:77], v[50:51], v[58:59]
	v_ashrrev_i32_e32 v65, 31, v64
	v_lshlrev_b64 v[74:75], 11, v[64:65]
	v_lshl_add_u64 v[74:75], s[14:15], 0, v[74:75]
	v_lshl_add_u64 v[74:75], v[74:75], 0, v[146:147]
	s_nop 0
	v_add_f32_e32 v50, v76, v76
	v_add_f32_e32 v51, v77, v77
	v_mul_f32_e32 v50, 0x3fb8aa3b, v50
	v_mul_f32_e32 v51, 0x3fb8aa3b, v51
	v_exp_f32_e32 v50, v50
	v_exp_f32_e32 v51, v51
	v_mul_f32_e32 v22, 0xbfb8aa3b, v22
	v_mul_f32_e32 v23, 0xbfb8aa3b, v23
	v_sub_f32_e32 v50, 1.0, v50
	v_sub_f32_e32 v51, 1.0, v51
	v_max_f32_e32 v50, 0, v50
	v_max_f32_e32 v51, 0, v51
	v_sqrt_f32_e32 v50, v50
	v_sqrt_f32_e32 v51, v51
	v_exp_f32_e32 v22, v22
	v_exp_f32_e32 v23, v23
	v_add_f32_e32 v10, v10, v70
	v_pk_mul_f32 v[50:51], v[54:55], v[50:51]
	v_add_f32_e32 v22, 1.0, v22
	v_add_f32_e32 v23, 1.0, v23
	v_rcp_f32_e32 v22, v22
	v_rcp_f32_e32 v23, v23
	v_add_f32_e32 v11, v11, v71
	v_mul_f32_e32 v10, 0xbfb8aa3b, v10
	v_mul_f32_e32 v11, 0xbfb8aa3b, v11
	v_exp_f32_e32 v10, v10
	v_exp_f32_e32 v11, v11
	v_add_f32_e32 v14, v14, v66
	v_add_f32_e32 v15, v15, v67
	v_add_f32_e32 v10, 1.0, v10
	v_add_f32_e32 v11, 1.0, v11
	v_rcp_f32_e32 v10, v10
	v_rcp_f32_e32 v11, v11
	v_mul_f32_e32 v14, 0xbfb8aa3b, v14
	v_mul_f32_e32 v15, 0xbfb8aa3b, v15
	v_exp_f32_e32 v14, v14
	v_exp_f32_e32 v15, v15
	v_add_f32_e32 v2, v2, v70
	v_add_f32_e32 v3, v3, v71
	v_add_f32_e32 v14, 1.0, v14
	v_add_f32_e32 v15, 1.0, v15
	v_rcp_f32_e32 v14, v14
	v_rcp_f32_e32 v15, v15
	v_mul_f32_e32 v2, 0xbfb8aa3b, v2
	v_mul_f32_e32 v3, 0xbfb8aa3b, v3
	v_exp_f32_e32 v2, v2
	v_exp_f32_e32 v3, v3
	v_add_f32_e32 v4, v4, v72
	v_add_f32_e32 v5, v5, v73
	v_add_f32_e32 v2, 1.0, v2
	v_add_f32_e32 v3, 1.0, v3
	v_rcp_f32_e32 v2, v2
	v_rcp_f32_e32 v3, v3
	v_mul_f32_e32 v4, 0xbfb8aa3b, v4
	v_mul_f32_e32 v5, 0xbfb8aa3b, v5
	v_exp_f32_e32 v4, v4
	v_pk_mul_f32 v[2:3], v[2:3], v[58:59]
	v_exp_f32_e32 v5, v5
	v_add_f32_e32 v6, v6, v66
	v_add_f32_e32 v4, 1.0, v4
	v_rcp_f32_e32 v4, v4
	v_add_f32_e32 v5, 1.0, v5
	v_rcp_f32_e32 v5, v5
	v_add_f32_e32 v7, v7, v67
	v_mul_f32_e32 v6, 0xbfb8aa3b, v6
	v_mul_f32_e32 v7, 0xbfb8aa3b, v7
	v_exp_f32_e32 v6, v6
	v_exp_f32_e32 v7, v7
	v_pk_mul_f32 v[4:5], v[4:5], v[60:61]
	v_add_f32_e32 v8, v8, v68
	v_add_f32_e32 v6, 1.0, v6
	v_add_f32_e32 v7, 1.0, v7
	v_rcp_f32_e32 v6, v6
	v_rcp_f32_e32 v7, v7
	v_add_f32_e32 v9, v9, v69
	v_mul_f32_e32 v8, 0xbfb8aa3b, v8
	v_mul_f32_e32 v9, 0xbfb8aa3b, v9
	v_exp_f32_e32 v8, v8
	v_exp_f32_e32 v9, v9
	s_nop 0
	v_mov_b32_e32 v74, v204
	v_mov_b32_e32 v75, v205
	v_lshlrev_b32_e32 v78, 16, v74
	v_and_b32_e32 v79, 0xffff0000, v74
	v_pk_mul_f32 v[54:55], v[50:51], v[78:79]
	v_add_f32_e32 v51, v56, v68
	v_mul_f32_e32 v51, 0xbfb8aa3b, v51
	v_exp_f32_e32 v51, v51
	v_add_f32_e32 v50, v52, v72
	v_mul_f32_e32 v50, 0xbfb8aa3b, v50
	v_exp_f32_e32 v50, v50
	v_add_f32_e32 v51, 1.0, v51
	v_rcp_f32_e32 v52, v51
	v_add_f32_e32 v51, v53, v73
	v_mul_f32_e32 v51, 0xbfb8aa3b, v51
	v_exp_f32_e32 v51, v51
	v_add_f32_e32 v50, 1.0, v50
	v_rcp_f32_e32 v50, v50
	v_add_f32_e32 v53, v57, v69
	v_add_f32_e32 v51, 1.0, v51
	v_rcp_f32_e32 v51, v51
	v_mul_f32_e32 v53, 0xbfb8aa3b, v53
	v_exp_f32_e32 v53, v53
	v_lshlrev_b32_e32 v74, 16, v75
	v_pk_mul_f32 v[56:57], v[50:51], v[60:61]
	v_and_b32_e32 v75, 0xffff0000, v75
	v_add_f32_e32 v50, v56, v56
	v_add_f32_e32 v51, v57, v57
	v_mul_f32_e32 v50, 0x3fb8aa3b, v50
	v_mul_f32_e32 v51, 0x3fb8aa3b, v51
	v_exp_f32_e32 v50, v50
	v_exp_f32_e32 v51, v51
	v_add_f32_e32 v53, 1.0, v53
	v_rcp_f32_e32 v53, v53
	v_sub_f32_e32 v50, 1.0, v50
	v_sub_f32_e32 v51, 1.0, v51
	v_max_f32_e32 v50, 0, v50
	v_max_f32_e32 v51, 0, v51
	v_sqrt_f32_e32 v50, v50
	v_sqrt_f32_e32 v51, v51
	v_cvt_pk_bf16_f32 v54, v54, v55
	v_add_f32_e32 v8, 1.0, v8
	v_add_f32_e32 v9, 1.0, v9
	v_pk_mul_f32 v[50:51], v[52:53], v[50:51]
	v_rcp_f32_e32 v8, v8
	v_pk_mul_f32 v[52:53], v[50:51], v[74:75]
	v_cvt_pk_bf16_f32 v75, v56, v57
	v_mad_i64_i32 v[56:57], s[6:7], v64, s84, v[130:131]
	v_lshl_add_u64 v[56:57], v[56:57], 0, v[62:63]
	v_add_co_u32_e32 v56, vcc, s69, v56
	v_add_u32_e32 v50, 16, v64
	v_cvt_pk_bf16_f32 v74, v76, v77
	v_addc_co_u32_e32 v57, vcc, 0, v57, vcc
	v_cvt_pk_bf16_f32 v55, v52, v53
	global_store_dwordx2 v[56:57], v[74:75], off offset:2048
	global_store_dwordx2 v[56:57], v[54:55], off
	v_pk_mul_f32 v[54:55], v[42:43], v[58:59]
	v_ashrrev_i32_e32 v51, 31, v50
	v_lshlrev_b64 v[52:53], 11, v[50:51]
	v_lshl_add_u64 v[52:53], s[14:15], 0, v[52:53]
	v_lshl_add_u64 v[52:53], v[52:53], 0, v[146:147]
	s_nop 0
	v_add_f32_e32 v42, v54, v54
	v_add_f32_e32 v43, v55, v55
	v_mul_f32_e32 v42, 0x3fb8aa3b, v42
	v_mul_f32_e32 v43, 0x3fb8aa3b, v43
	v_exp_f32_e32 v42, v42
	v_exp_f32_e32 v43, v43
	v_rcp_f32_e32 v9, v9
	s_mov_b32 s2, s22
	v_sub_f32_e32 v42, 1.0, v42
	v_sub_f32_e32 v43, 1.0, v43
	v_max_f32_e32 v42, 0, v42
	v_max_f32_e32 v43, 0, v43
	v_sqrt_f32_e32 v42, v42
	v_sqrt_f32_e32 v43, v43
	s_nop 0
	v_mov_b32_e32 v52, v206
	v_mov_b32_e32 v53, v207
	v_lshlrev_b32_e32 v56, 16, v52
	v_and_b32_e32 v57, 0xffff0000, v52
	v_pk_mul_f32 v[42:43], v[46:47], v[42:43]
	v_lshlrev_b32_e32 v52, 16, v53
	v_pk_mul_f32 v[46:47], v[42:43], v[56:57]
	v_add_f32_e32 v43, v48, v68
	v_mul_f32_e32 v43, 0xbfb8aa3b, v43
	v_exp_f32_e32 v43, v43
	v_add_f32_e32 v42, v44, v72
	v_mul_f32_e32 v42, 0xbfb8aa3b, v42
	v_exp_f32_e32 v42, v42
	v_add_f32_e32 v43, 1.0, v43
	v_rcp_f32_e32 v44, v43
	v_add_f32_e32 v43, v45, v73
	v_mul_f32_e32 v43, 0xbfb8aa3b, v43
	v_exp_f32_e32 v43, v43
	v_add_f32_e32 v42, 1.0, v42
	v_rcp_f32_e32 v42, v42
	v_add_f32_e32 v45, v49, v69
	v_add_f32_e32 v43, 1.0, v43
	v_rcp_f32_e32 v43, v43
	v_mul_f32_e32 v45, 0xbfb8aa3b, v45
	v_exp_f32_e32 v45, v45
	v_and_b32_e32 v53, 0xffff0000, v53
	v_pk_mul_f32 v[48:49], v[42:43], v[60:61]
	v_cvt_pk_bf16_f32 v46, v46, v47
	v_add_f32_e32 v42, v48, v48
	v_add_f32_e32 v43, v49, v49
	v_mul_f32_e32 v42, 0x3fb8aa3b, v42
	v_mul_f32_e32 v43, 0x3fb8aa3b, v43
	v_exp_f32_e32 v42, v42
	v_exp_f32_e32 v43, v43
	v_add_f32_e32 v45, 1.0, v45
	v_rcp_f32_e32 v45, v45
	v_sub_f32_e32 v42, 1.0, v42
	v_sub_f32_e32 v43, 1.0, v43
	v_max_f32_e32 v42, 0, v42
	v_max_f32_e32 v43, 0, v43
	v_sqrt_f32_e32 v42, v42
	v_sqrt_f32_e32 v43, v43
	s_nop 0
	v_pk_mul_f32 v[42:43], v[44:45], v[42:43]
	s_nop 0
	v_pk_mul_f32 v[44:45], v[42:43], v[52:53]
	v_cvt_pk_bf16_f32 v53, v48, v49
	v_mad_i64_i32 v[48:49], s[6:7], v50, s84, v[130:131]
	v_lshl_add_u64 v[48:49], v[48:49], 0, v[62:63]
	v_add_co_u32_e32 v48, vcc, s69, v48
	v_add_u32_e32 v42, 16, v50
	v_cvt_pk_bf16_f32 v52, v54, v55
	v_addc_co_u32_e32 v49, vcc, 0, v49, vcc
	v_cvt_pk_bf16_f32 v47, v44, v45
	global_store_dwordx2 v[48:49], v[52:53], off offset:2048
	global_store_dwordx2 v[48:49], v[46:47], off
	v_pk_mul_f32 v[46:47], v[34:35], v[58:59]
	v_ashrrev_i32_e32 v43, 31, v42
	v_lshlrev_b64 v[44:45], 11, v[42:43]
	v_lshl_add_u64 v[44:45], s[14:15], 0, v[44:45]
	v_lshl_add_u64 v[44:45], v[44:45], 0, v[146:147]
	s_nop 0
	v_add_f32_e32 v34, v46, v46
	v_add_f32_e32 v35, v47, v47
	v_mul_f32_e32 v34, 0x3fb8aa3b, v34
	v_mul_f32_e32 v35, 0x3fb8aa3b, v35
	v_exp_f32_e32 v34, v34
	v_exp_f32_e32 v35, v35
	v_sub_f32_e32 v34, 1.0, v34
	v_sub_f32_e32 v35, 1.0, v35
	v_max_f32_e32 v34, 0, v34
	v_max_f32_e32 v35, 0, v35
	v_sqrt_f32_e32 v34, v34
	v_sqrt_f32_e32 v35, v35
	s_nop 0
	v_mov_b32_e32 v44, v208
	v_mov_b32_e32 v45, v209
	v_lshlrev_b32_e32 v48, 16, v44
	v_and_b32_e32 v49, 0xffff0000, v44
	v_pk_mul_f32 v[34:35], v[38:39], v[34:35]
	v_lshlrev_b32_e32 v44, 16, v45
	v_pk_mul_f32 v[38:39], v[34:35], v[48:49]
	v_add_f32_e32 v35, v40, v68
	v_mul_f32_e32 v35, 0xbfb8aa3b, v35
	v_exp_f32_e32 v35, v35
	v_add_f32_e32 v34, v36, v72
	v_mul_f32_e32 v34, 0xbfb8aa3b, v34
	v_exp_f32_e32 v34, v34
	v_add_f32_e32 v35, 1.0, v35
	v_rcp_f32_e32 v36, v35
	v_add_f32_e32 v35, v37, v73
	v_mul_f32_e32 v35, 0xbfb8aa3b, v35
	v_exp_f32_e32 v35, v35
	v_add_f32_e32 v34, 1.0, v34
	v_rcp_f32_e32 v34, v34
	v_add_f32_e32 v37, v41, v69
	v_add_f32_e32 v35, 1.0, v35
	v_rcp_f32_e32 v35, v35
	v_mul_f32_e32 v37, 0xbfb8aa3b, v37
	v_exp_f32_e32 v37, v37
	v_and_b32_e32 v45, 0xffff0000, v45
	v_pk_mul_f32 v[40:41], v[34:35], v[60:61]
	v_cvt_pk_bf16_f32 v38, v38, v39
	v_add_f32_e32 v34, v40, v40
	v_add_f32_e32 v35, v41, v41
	v_mul_f32_e32 v34, 0x3fb8aa3b, v34
	v_mul_f32_e32 v35, 0x3fb8aa3b, v35
	v_exp_f32_e32 v34, v34
	v_exp_f32_e32 v35, v35
	v_add_f32_e32 v37, 1.0, v37
	v_rcp_f32_e32 v37, v37
	v_sub_f32_e32 v34, 1.0, v34
	v_sub_f32_e32 v35, 1.0, v35
	v_max_f32_e32 v34, 0, v34
	v_max_f32_e32 v35, 0, v35
	v_sqrt_f32_e32 v34, v34
	v_sqrt_f32_e32 v35, v35
	s_nop 0
	v_pk_mul_f32 v[34:35], v[36:37], v[34:35]
	s_nop 0
	v_pk_mul_f32 v[36:37], v[34:35], v[44:45]
	v_cvt_pk_bf16_f32 v45, v40, v41
	v_mad_i64_i32 v[40:41], s[6:7], v42, s84, v[130:131]
	v_lshl_add_u64 v[40:41], v[40:41], 0, v[62:63]
	v_add_co_u32_e32 v40, vcc, s69, v40
	v_add_u32_e32 v34, 0x50, v42
	v_cvt_pk_bf16_f32 v44, v46, v47
	v_addc_co_u32_e32 v41, vcc, 0, v41, vcc
	v_cvt_pk_bf16_f32 v39, v36, v37
	global_store_dwordx2 v[40:41], v[44:45], off offset:2048
	global_store_dwordx2 v[40:41], v[38:39], off
	v_pk_mul_f32 v[38:39], v[26:27], v[58:59]
	v_ashrrev_i32_e32 v35, 31, v34
	v_lshlrev_b64 v[36:37], 11, v[34:35]
	v_lshl_add_u64 v[36:37], s[14:15], 0, v[36:37]
	v_lshl_add_u64 v[36:37], v[36:37], 0, v[146:147]
	s_nop 0
	v_add_f32_e32 v26, v38, v38
	v_add_f32_e32 v27, v39, v39
	v_mul_f32_e32 v26, 0x3fb8aa3b, v26
	v_mul_f32_e32 v27, 0x3fb8aa3b, v27
	v_exp_f32_e32 v26, v26
	v_exp_f32_e32 v27, v27
	v_sub_f32_e32 v26, 1.0, v26
	v_sub_f32_e32 v27, 1.0, v27
	v_max_f32_e32 v26, 0, v26
	v_max_f32_e32 v27, 0, v27
	v_sqrt_f32_e32 v26, v26
	v_sqrt_f32_e32 v27, v27
	s_nop 0
	v_mov_b32_e32 v36, v210
	v_mov_b32_e32 v37, v211
	v_lshlrev_b32_e32 v40, 16, v36
	v_and_b32_e32 v41, 0xffff0000, v36
	v_pk_mul_f32 v[26:27], v[30:31], v[26:27]
	v_lshlrev_b32_e32 v36, 16, v37
	v_pk_mul_f32 v[30:31], v[26:27], v[40:41]
	v_add_f32_e32 v27, v32, v68
	v_mul_f32_e32 v27, 0xbfb8aa3b, v27
	v_exp_f32_e32 v27, v27
	v_add_f32_e32 v26, v28, v72
	v_mul_f32_e32 v26, 0xbfb8aa3b, v26
	v_exp_f32_e32 v26, v26
	v_add_f32_e32 v27, 1.0, v27
	v_rcp_f32_e32 v28, v27
	v_add_f32_e32 v27, v29, v73
	v_mul_f32_e32 v27, 0xbfb8aa3b, v27
	v_exp_f32_e32 v27, v27
	v_add_f32_e32 v26, 1.0, v26
	v_rcp_f32_e32 v26, v26
	v_add_f32_e32 v29, v33, v69
	v_add_f32_e32 v27, 1.0, v27
	v_rcp_f32_e32 v27, v27
	v_mul_f32_e32 v29, 0xbfb8aa3b, v29
	v_exp_f32_e32 v29, v29
	v_and_b32_e32 v37, 0xffff0000, v37
	v_pk_mul_f32 v[32:33], v[26:27], v[60:61]
	v_cvt_pk_bf16_f32 v30, v30, v31
	v_add_f32_e32 v26, v32, v32
	v_add_f32_e32 v27, v33, v33
	v_mul_f32_e32 v26, 0x3fb8aa3b, v26
	v_mul_f32_e32 v27, 0x3fb8aa3b, v27
	v_exp_f32_e32 v26, v26
	v_exp_f32_e32 v27, v27
	v_add_f32_e32 v29, 1.0, v29
	v_rcp_f32_e32 v29, v29
	v_sub_f32_e32 v26, 1.0, v26
	v_sub_f32_e32 v27, 1.0, v27
	v_max_f32_e32 v26, 0, v26
	v_max_f32_e32 v27, 0, v27
	v_sqrt_f32_e32 v26, v26
	v_sqrt_f32_e32 v27, v27
	s_nop 0
	v_pk_mul_f32 v[26:27], v[28:29], v[26:27]
	s_nop 0
	v_pk_mul_f32 v[28:29], v[26:27], v[36:37]
	v_cvt_pk_bf16_f32 v37, v32, v33
	v_mad_i64_i32 v[32:33], s[6:7], v34, s84, v[130:131]
	v_lshl_add_u64 v[32:33], v[32:33], 0, v[62:63]
	v_add_co_u32_e32 v32, vcc, s69, v32
	v_add_u32_e32 v26, 16, v34
	v_cvt_pk_bf16_f32 v36, v38, v39
	v_addc_co_u32_e32 v33, vcc, 0, v33, vcc
	v_cvt_pk_bf16_f32 v31, v28, v29
	global_store_dwordx2 v[32:33], v[36:37], off offset:2048
	global_store_dwordx2 v[32:33], v[30:31], off
	v_pk_mul_f32 v[30:31], v[18:19], v[58:59]
	v_ashrrev_i32_e32 v27, 31, v26
	v_lshlrev_b64 v[28:29], 11, v[26:27]
	v_lshl_add_u64 v[28:29], s[14:15], 0, v[28:29]
	v_lshl_add_u64 v[28:29], v[28:29], 0, v[146:147]
	s_nop 0
	v_add_f32_e32 v18, v30, v30
	v_add_f32_e32 v19, v31, v31
	v_mul_f32_e32 v18, 0x3fb8aa3b, v18
	v_mul_f32_e32 v19, 0x3fb8aa3b, v19
	v_exp_f32_e32 v18, v18
	v_exp_f32_e32 v19, v19
	v_sub_f32_e32 v18, 1.0, v18
	v_sub_f32_e32 v19, 1.0, v19
	v_max_f32_e32 v18, 0, v18
	v_max_f32_e32 v19, 0, v19
	v_sqrt_f32_e32 v18, v18
	v_sqrt_f32_e32 v19, v19
	s_nop 0
	v_mov_b32_e32 v28, v212
	v_mov_b32_e32 v29, v213
	v_lshlrev_b32_e32 v32, 16, v28
	v_and_b32_e32 v33, 0xffff0000, v28
	v_pk_mul_f32 v[18:19], v[22:23], v[18:19]
	v_lshlrev_b32_e32 v28, 16, v29
	v_pk_mul_f32 v[22:23], v[18:19], v[32:33]
	v_add_f32_e32 v19, v24, v68
	v_mul_f32_e32 v19, 0xbfb8aa3b, v19
	v_exp_f32_e32 v19, v19
	v_add_f32_e32 v18, v20, v72
	v_mul_f32_e32 v18, 0xbfb8aa3b, v18
	v_exp_f32_e32 v18, v18
	v_add_f32_e32 v19, 1.0, v19
	v_rcp_f32_e32 v20, v19
	v_add_f32_e32 v19, v21, v73
	v_mul_f32_e32 v19, 0xbfb8aa3b, v19
	v_exp_f32_e32 v19, v19
	v_add_f32_e32 v18, 1.0, v18
	v_rcp_f32_e32 v18, v18
	v_add_f32_e32 v21, v25, v69
	v_add_f32_e32 v19, 1.0, v19
	v_rcp_f32_e32 v19, v19
	v_mul_f32_e32 v21, 0xbfb8aa3b, v21
	v_exp_f32_e32 v21, v21
	v_and_b32_e32 v29, 0xffff0000, v29
	v_pk_mul_f32 v[24:25], v[18:19], v[60:61]
	v_cvt_pk_bf16_f32 v22, v22, v23
	v_add_f32_e32 v18, v24, v24
	v_add_f32_e32 v19, v25, v25
	v_mul_f32_e32 v18, 0x3fb8aa3b, v18
	v_mul_f32_e32 v19, 0x3fb8aa3b, v19
	v_exp_f32_e32 v18, v18
	v_exp_f32_e32 v19, v19
	v_add_f32_e32 v21, 1.0, v21
	v_rcp_f32_e32 v21, v21
	v_sub_f32_e32 v18, 1.0, v18
	v_sub_f32_e32 v19, 1.0, v19
	v_max_f32_e32 v18, 0, v18
	v_max_f32_e32 v19, 0, v19
	v_sqrt_f32_e32 v18, v18
	v_sqrt_f32_e32 v19, v19
	s_nop 0
	v_pk_mul_f32 v[18:19], v[20:21], v[18:19]
	s_nop 0
	v_pk_mul_f32 v[20:21], v[18:19], v[28:29]
	v_cvt_pk_bf16_f32 v29, v24, v25
	v_mad_i64_i32 v[24:25], s[6:7], v26, s84, v[130:131]
	v_lshl_add_u64 v[24:25], v[24:25], 0, v[62:63]
	v_add_co_u32_e32 v24, vcc, s69, v24
	v_add_u32_e32 v18, 16, v26
	v_cvt_pk_bf16_f32 v28, v30, v31
	v_addc_co_u32_e32 v25, vcc, 0, v25, vcc
	v_cvt_pk_bf16_f32 v23, v20, v21
	global_store_dwordx2 v[24:25], v[28:29], off offset:2048
	global_store_dwordx2 v[24:25], v[22:23], off
	v_pk_mul_f32 v[22:23], v[10:11], v[58:59]
	v_ashrrev_i32_e32 v19, 31, v18
	v_lshlrev_b64 v[20:21], 11, v[18:19]
	v_lshl_add_u64 v[20:21], s[14:15], 0, v[20:21]
	v_lshl_add_u64 v[20:21], v[20:21], 0, v[146:147]
	s_nop 0
	v_add_f32_e32 v10, v22, v22
	v_add_f32_e32 v11, v23, v23
	v_mul_f32_e32 v10, 0x3fb8aa3b, v10
	v_mul_f32_e32 v11, 0x3fb8aa3b, v11
	v_exp_f32_e32 v10, v10
	v_exp_f32_e32 v11, v11
	v_sub_f32_e32 v10, 1.0, v10
	v_sub_f32_e32 v11, 1.0, v11
	v_max_f32_e32 v10, 0, v10
	v_max_f32_e32 v11, 0, v11
	v_sqrt_f32_e32 v10, v10
	v_sqrt_f32_e32 v11, v11
	s_nop 0
	v_mov_b32_e32 v20, v214
	v_mov_b32_e32 v21, v215
	v_lshlrev_b32_e32 v24, 16, v20
	v_and_b32_e32 v25, 0xffff0000, v20
	v_pk_mul_f32 v[10:11], v[14:15], v[10:11]
	v_lshlrev_b32_e32 v20, 16, v21
	v_pk_mul_f32 v[14:15], v[10:11], v[24:25]
	v_add_f32_e32 v11, v16, v68
	v_mul_f32_e32 v11, 0xbfb8aa3b, v11
	v_exp_f32_e32 v11, v11
	v_add_f32_e32 v10, v12, v72
	v_mul_f32_e32 v10, 0xbfb8aa3b, v10
	v_exp_f32_e32 v10, v10
	v_add_f32_e32 v11, 1.0, v11
	v_rcp_f32_e32 v12, v11
	v_add_f32_e32 v11, v13, v73
	v_mul_f32_e32 v11, 0xbfb8aa3b, v11
	v_exp_f32_e32 v11, v11
	v_add_f32_e32 v10, 1.0, v10
	v_rcp_f32_e32 v10, v10
	v_add_f32_e32 v13, v17, v69
	v_add_f32_e32 v11, 1.0, v11
	v_rcp_f32_e32 v11, v11
	v_mul_f32_e32 v13, 0xbfb8aa3b, v13
	v_exp_f32_e32 v13, v13
	v_and_b32_e32 v21, 0xffff0000, v21
	v_pk_mul_f32 v[16:17], v[10:11], v[60:61]
	v_cvt_pk_bf16_f32 v14, v14, v15
	v_add_f32_e32 v10, v16, v16
	v_add_f32_e32 v11, v17, v17
	v_mul_f32_e32 v10, 0x3fb8aa3b, v10
	v_mul_f32_e32 v11, 0x3fb8aa3b, v11
	v_exp_f32_e32 v10, v10
	v_exp_f32_e32 v11, v11
	v_add_f32_e32 v13, 1.0, v13
	v_rcp_f32_e32 v13, v13
	v_sub_f32_e32 v10, 1.0, v10
	v_sub_f32_e32 v11, 1.0, v11
	v_max_f32_e32 v10, 0, v10
	v_max_f32_e32 v11, 0, v11
	v_sqrt_f32_e32 v10, v10
	v_sqrt_f32_e32 v11, v11
	s_nop 0
	v_pk_mul_f32 v[10:11], v[12:13], v[10:11]
	s_nop 0
	v_pk_mul_f32 v[12:13], v[10:11], v[20:21]
	v_cvt_pk_bf16_f32 v21, v16, v17
	v_mad_i64_i32 v[16:17], s[6:7], v18, s84, v[130:131]
	v_lshl_add_u64 v[16:17], v[16:17], 0, v[62:63]
	v_add_co_u32_e32 v16, vcc, s69, v16
	v_add_u32_e32 v10, 16, v18
	v_cvt_pk_bf16_f32 v20, v22, v23
	v_addc_co_u32_e32 v17, vcc, 0, v17, vcc
	v_cvt_pk_bf16_f32 v15, v12, v13
	global_store_dwordx2 v[16:17], v[20:21], off offset:2048
	global_store_dwordx2 v[16:17], v[14:15], off
	s_nop 0
	v_ashrrev_i32_e32 v11, 31, v10
	v_lshlrev_b64 v[12:13], 11, v[10:11]
	v_lshl_add_u64 v[12:13], s[14:15], 0, v[12:13]
	v_lshl_add_u64 v[12:13], v[12:13], 0, v[146:147]
	s_nop 0
	v_add_f32_e32 v11, v2, v2
	v_mul_f32_e32 v11, 0x3fb8aa3b, v11
	v_exp_f32_e32 v11, v11
	v_cvt_pk_bf16_f32 v2, v2, v3
	v_sub_f32_e32 v11, 1.0, v11
	v_max_f32_e32 v11, 0, v11
	v_sqrt_f32_e32 v14, v11
	v_add_f32_e32 v11, v3, v3
	v_mul_f32_e32 v11, 0x3fb8aa3b, v11
	v_exp_f32_e32 v11, v11
	v_cvt_pk_bf16_f32 v3, v4, v5
	v_sub_f32_e32 v11, 1.0, v11
	v_max_f32_e32 v11, 0, v11
	v_sqrt_f32_e32 v15, v11
	v_add_f32_e32 v11, v4, v4
	v_mul_f32_e32 v11, 0x3fb8aa3b, v11
	v_exp_f32_e32 v11, v11
	v_pk_mul_f32 v[6:7], v[6:7], v[14:15]
	v_sub_f32_e32 v11, 1.0, v11
	v_max_f32_e32 v11, 0, v11
	v_sqrt_f32_e32 v14, v11
	v_add_f32_e32 v11, v5, v5
	v_mul_f32_e32 v11, 0x3fb8aa3b, v11
	v_exp_f32_e32 v11, v11
	v_mad_i64_i32 v[4:5], s[6:7], v10, s84, v[130:131]
	v_lshl_add_u64 v[4:5], v[4:5], 0, v[62:63]
	v_sub_f32_e32 v11, 1.0, v11
	v_max_f32_e32 v11, 0, v11
	v_sqrt_f32_e32 v15, v11
	v_add_co_u32_e32 v4, vcc, s69, v4
	v_pk_mul_f32 v[8:9], v[8:9], v[14:15]
	s_nop 0
	v_addc_co_u32_e32 v5, vcc, 0, v5, vcc
	global_store_dwordx2 v[4:5], v[2:3], off offset:2048
	s_andn2_b64 vcc, exec, s[4:5]
	s_nop 0
	v_mov_b32_e32 v12, v216
	v_mov_b32_e32 v13, v217
	v_lshlrev_b32_e32 v16, 16, v12
	v_and_b32_e32 v17, 0xffff0000, v12
	v_lshlrev_b32_e32 v12, 16, v13
	v_and_b32_e32 v13, 0xffff0000, v13
	v_pk_mul_f32 v[6:7], v[6:7], v[16:17]
	v_pk_mul_f32 v[8:9], v[8:9], v[12:13]
	v_cvt_pk_bf16_f32 v2, v6, v7
	v_cvt_pk_bf16_f32 v3, v8, v9
	global_store_dwordx2 v[4:5], v[2:3], off
	s_cbranch_vccz .LBB0_1214
